# P10 top-16 selection rewritten: non-destructive threshold rounds (key minus previous max, unsigned wrap) replace compare+select elimination; dn_sample conv loads batched
# speedup vs baseline: 1.1950x; 1.0118x over previous
; DI float bf2f(u16 h) { return __uint_as_float(((unsigned)h) << 16); }
; DI float siluf(float x) { return x / (1.f + __expf(-x)); }
; DI void dn_sample(const Params& p, int item, char* smem) {
;     ...
;   for (int c = tid; c < 384; c += 256) {
;     const int part = c >> 7, cc = c & 127;
;     const int col = part * 512 + h * 128 + cc;
;     float xp[7];
; #pragma unroll
;     for (int j = 0; j < 3; ++j) xp[j] = p.state_conv[((size_t)b * 3 + j) * 1536 + col];
; #pragma unroll
;     for (int j = 0; j < 4; ++j) xp[3 + j] = bf2f(p.proj[((size_t)MP + b * 4 + j) * NP + col]);
;     const float w0 = p.conv_w[col], w1 = p.conv_w[1536 + col], w2 = p.conv_w[3072 + col], w3 = p.conv_w[4608 + col];
;     float* dst = part == 0 ? sq : (part == 1 ? sk : sv);
; #pragma unroll
;     for (int t = 0; t < 4; ++t) dst[t * 128 + cc] = siluf(w0 * xp[t] + w1 * xp[t + 1] + w2 * xp[t + 2] + w3 * xp[t + 3]);
;   }
.LBB0_359:
	v_add_u32_e32 v18, v213, v1
	v_mov_b32_e32 v19, v0
	v_lshl_add_u64 v[20:21], v[18:19], 2, v[2:3]
	flat_load_dword v22, v[20:21]
	v_add_u32_e32 v20, 0x600, v18
	v_mov_b32_e32 v21, v0
	v_add_u32_e32 v18, 0xc00, v18
	v_lshl_add_u64 v[20:21], v[20:21], 2, v[2:3]
	v_lshl_add_u64 v[18:19], v[18:19], 2, v[2:3]
	flat_load_dword v20, v[20:21]
	s_nop 0
	flat_load_dword v21, v[18:19]
	s_nop 0
	flat_load_ushort v23, v[12:13]
	v_mov_b32_e32 v19, v0
	s_movk_i32 s0, 0xb800
	v_mov_b32_e32 v29, 0x1000
	v_mov_b32_e32 v30, 0x800
	v_add_u32_e32 v1, 0x400, v1
	v_lshl_add_u64 v[12:13], v[12:13], 0, s[38:39]
	flat_load_ushort v24, v[8:9]
	v_lshl_add_u64 v[8:9], v[8:9], 0, s[38:39]
	flat_load_ushort v25, v[6:7]
	v_lshl_add_u64 v[6:7], v[6:7], 0, s[38:39]
	v_add_u32_e32 v18, v213, v16
	v_lshl_add_u64 v[18:19], v[18:19], 1, v[4:5]
	flat_load_ushort v26, v[18:19]
	v_add_u32_e32 v16, 0x400, v16
	v_add_co_u32_e32 v18, vcc, s0, v14
	s_movk_i32 s0, 0xd000
	s_nop 0
	v_addc_co_u32_e32 v19, vcc, -1, v15, vcc
	flat_load_dword v27, v[18:19]
	v_add_co_u32_e32 v18, vcc, s0, v14
	s_movk_i32 s0, 0xe800
	s_nop 0
	v_addc_co_u32_e32 v19, vcc, -1, v15, vcc
	flat_load_dword v28, v[18:19]
	v_add_co_u32_e32 v18, vcc, s0, v14
	v_cmp_lt_u32_e64 s[0:1], s56, v17
	s_nop 0
	v_addc_co_u32_e32 v19, vcc, -1, v15, vcc
	flat_load_dword v18, v[18:19]
	s_nop 0
	flat_load_dword v19, v[14:15]
	v_cmp_eq_u32_e32 vcc, s18, v213
	s_addk_i32 s18, 0xfc00
	v_add_u32_e32 v17, 0x100, v17
	v_cndmask_b32_e32 v29, v29, v30, vcc
	v_cndmask_b32_e64 v29, 0, v29, s[0:1]
	v_lshl_or_b32 v29, v62, 2, v29
	v_lshl_add_u64 v[14:15], v[14:15], 0, s[40:41]
	s_or_b64 s[14:15], s[0:1], s[14:15]
	s_waitcnt vmcnt(0) lgkmcnt(0)
	v_lshlrev_b32_e32 v23, 16, v23
	v_lshlrev_b32_e32 v24, 16, v24
	v_lshlrev_b32_e32 v25, 16, v25
	v_lshlrev_b32_e32 v26, 16, v26
	v_mul_f32_e32 v30, v20, v28
	v_fmac_f32_e32 v30, v22, v27
	v_fmac_f32_e32 v30, v21, v18
	v_fmac_f32_e32 v30, v19, v23
	v_mul_f32_e32 v22, 0xbfb8aa3b, v30
	v_exp_f32_e32 v22, v22
	s_nop 0
	v_add_f32_e32 v22, 1.0, v22
	v_div_scale_f32 v31, s[20:21], v22, v22, v30
	v_rcp_f32_e32 v32, v31
	s_nop 0
	v_fma_f32 v33, -v31, v32, 1.0
	v_fmac_f32_e32 v32, v33, v32
	v_div_scale_f32 v33, vcc, v30, v22, v30
	v_mul_f32_e32 v34, v33, v32
	v_fma_f32 v35, -v31, v34, v33
	v_fmac_f32_e32 v34, v35, v32
	v_fma_f32 v31, -v31, v34, v33
	v_div_fmas_f32 v31, v31, v32, v34
	v_div_fixup_f32 v22, v31, v22, v30
	v_mul_f32_e32 v30, v21, v28
	v_fmac_f32_e32 v30, v20, v27
	v_fmac_f32_e32 v30, v18, v23
	v_fmac_f32_e32 v30, v19, v24
	v_mul_f32_e32 v20, 0xbfb8aa3b, v30
	v_exp_f32_e32 v20, v20
	s_nop 0
	v_add_f32_e32 v20, 1.0, v20
	v_div_scale_f32 v31, s[20:21], v20, v20, v30
	v_rcp_f32_e32 v32, v31
	s_nop 0
	v_fma_f32 v33, -v31, v32, 1.0
	v_fmac_f32_e32 v32, v33, v32
	v_div_scale_f32 v33, vcc, v30, v20, v30
	v_mul_f32_e32 v34, v33, v32
	v_fma_f32 v35, -v31, v34, v33
	v_fmac_f32_e32 v34, v35, v32
	v_fma_f32 v31, -v31, v34, v33
	v_div_fmas_f32 v31, v31, v32, v34
	v_div_fixup_f32 v20, v31, v20, v30
	ds_write2st64_b32 v29, v22, v20 offset1:2
	v_mul_f32_e32 v20, v28, v23
	v_fmac_f32_e32 v20, v21, v27
	v_fmac_f32_e32 v20, v18, v24
	v_fmac_f32_e32 v20, v19, v25
	v_mul_f32_e32 v21, 0xbfb8aa3b, v20
	v_exp_f32_e32 v21, v21
	s_nop 0
	v_add_f32_e32 v21, 1.0, v21
	v_div_scale_f32 v22, s[20:21], v21, v21, v20
	v_rcp_f32_e32 v30, v22
	s_nop 0
	v_fma_f32 v31, -v22, v30, 1.0
	v_fmac_f32_e32 v30, v31, v30
	v_div_scale_f32 v31, vcc, v20, v21, v20
	v_mul_f32_e32 v32, v31, v30
	v_fma_f32 v33, -v22, v32, v31
	v_fmac_f32_e32 v32, v33, v30
	v_fma_f32 v22, -v22, v32, v31
	v_div_fmas_f32 v22, v22, v30, v32
	v_div_fixup_f32 v20, v22, v21, v20
	v_mul_f32_e32 v21, v28, v24
	v_fmac_f32_e32 v21, v27, v23
	v_fmac_f32_e32 v21, v18, v25
	v_fmac_f32_e32 v21, v19, v26
	v_mul_f32_e32 v18, 0xbfb8aa3b, v21
	v_exp_f32_e32 v18, v18
	s_nop 0
	v_add_f32_e32 v18, 1.0, v18
	v_div_scale_f32 v19, s[20:21], v18, v18, v21
	v_rcp_f32_e32 v22, v19
	s_nop 0
	v_fma_f32 v23, -v19, v22, 1.0
	v_fmac_f32_e32 v22, v23, v22
	v_div_scale_f32 v23, vcc, v21, v18, v21
	v_mul_f32_e32 v24, v23, v22
	v_fma_f32 v25, -v19, v24, v23
	v_fmac_f32_e32 v24, v25, v22
	v_fma_f32 v19, -v19, v24, v23
	v_div_fmas_f32 v19, v19, v22, v24
	v_div_fixup_f32 v18, v19, v18, v21
	ds_write2st64_b32 v29, v20, v18 offset0:4 offset1:6
	s_andn2_b64 exec, exec, s[14:15]
	s_cbranch_execnz .LBB0_359

; #define MFMA(a, b, c) __builtin_amdgcn_mfma_f32_16x16x32_bf16((a), (b), (c), 0, 0, 0)
; DI unsigned ordf(float f) { unsigned u = __float_as_uint(f); return (u & 0x80000000u) ? ~u : (u | 0x80000000u); }
; DI void peer_topk_wave(const Params& p, int item, unsigned* lds  ) {
;     ...
; #pragma unroll
;     for (int mt = 0; mt < 8; ++mt) {
;       f32x4 a = (f32x4){0.f, 0.f, 0.f, 0.f};
; #pragma unroll
;       for (int ks = 0; ks < 4; ++ks) {
;         bf16x8 kf = *(const bf16x8*)&sk[(mt * 16 + r) * 128 + ks * 32 + kg * 8];
;         a = MFMA(kf, qf[ks], a);
;       }
; #pragma unroll
;       for (int j = 0; j < 4; ++j) kk[mt * 4 + j] = (ordf(a[j]) & ~127u) | (unsigned)(mt * 16 + kg * 4 + j);
;     }
.Lp10q_done0:
	v_readfirstlane_b32 s0, v86
	v_readfirstlane_b32 s1, v87
	s_nop 3
	s_add_u32 s2, s0, 0x0
	s_addc_u32 s3, s1, 0
	ds_read_b128 v[24:27], v241 offset:0
	ds_read_b128 v[28:31], v241 offset:64
	ds_read_b128 v[32:35], v241 offset:128
	ds_read_b128 v[36:39], v241 offset:192
	s_add_u32 s2, s0, 0x1000
	s_addc_u32 s3, s1, 0
	ds_read_b128 v[40:43], v241 offset:4352
	ds_read_b128 v[44:47], v241 offset:4416
	ds_read_b128 v[48:51], v241 offset:4480
	ds_read_b128 v[52:55], v241 offset:4544
	s_add_u32 s2, s0, 0x2000
	s_addc_u32 s3, s1, 0
	ds_read_b128 v[56:59], v241 offset:8704
	ds_read_b128 v[60:63], v241 offset:8768
	ds_read_b128 v[64:67], v241 offset:8832
	ds_read_b128 v[68:71], v241 offset:8896
	s_add_u32 s2, s0, 0x3000
	s_addc_u32 s3, s1, 0
	ds_read_b128 v[72:75], v241 offset:13056
	ds_read_b128 v[76:79], v241 offset:13120
	ds_read_b128 v[80:83], v241 offset:13184
	s_waitcnt vmcnt(0) lgkmcnt(11)
	v_mfma_f32_16x16x32_bf16 v[190:193], v[24:27], v[12:15], 0
	v_mfma_f32_16x16x32_bf16 v[190:193], v[28:31], v[8:11], v[190:193]
	v_mfma_f32_16x16x32_bf16 v[190:193], v[32:35], v[4:7], v[190:193]
	v_mfma_f32_16x16x32_bf16 v[190:193], v[36:39], v[0:3], v[190:193]
	ds_read_b128 v[24:27], v241 offset:13248
	s_add_u32 s2, s0, 0x4000
	s_addc_u32 s3, s1, 0
	ds_read_b128 v[28:31], v241 offset:17408
	ds_read_b128 v[32:35], v241 offset:17472
	ds_read_b128 v[36:39], v241 offset:17536
	s_waitcnt lgkmcnt(11)
	v_mfma_f32_16x16x32_bf16 v[198:201], v[40:43], v[12:15], 0
	v_mfma_f32_16x16x32_bf16 v[198:201], v[44:47], v[8:11], v[198:201]
	v_mfma_f32_16x16x32_bf16 v[198:201], v[48:51], v[4:7], v[198:201]
	v_mfma_f32_16x16x32_bf16 v[198:201], v[52:55], v[0:3], v[198:201]
	ds_read_b128 v[40:43], v241 offset:17600
	s_add_u32 s2, s0, 0x5000
	s_addc_u32 s3, s1, 0
	ds_read_b128 v[44:47], v241 offset:21760
	ds_read_b128 v[48:51], v241 offset:21824
	ds_read_b128 v[52:55], v241 offset:21888
	s_nop 7
	s_nop 3
	v_ashrrev_i32_e32 v197, 31, v190
	v_or_b32_e32 v197, 0x80000000, v197
	v_xor_b32_e32 v197, v190, v197
	v_and_or_b32 v147, v197, s80, v170
	v_ashrrev_i32_e32 v202, 31, v191
	v_or_b32_e32 v202, 0x80000000, v202
	v_xor_b32_e32 v202, v191, v202
	v_and_or_b32 v148, v202, s80, v113
	v_ashrrev_i32_e32 v197, 31, v192
	v_or_b32_e32 v197, 0x80000000, v197
	v_xor_b32_e32 v197, v192, v197
	v_and_or_b32 v149, v197, s80, v114
	v_ashrrev_i32_e32 v202, 31, v193
	v_or_b32_e32 v202, 0x80000000, v202
	v_xor_b32_e32 v202, v193, v202
	v_and_or_b32 v150, v202, s80, v115
	s_waitcnt lgkmcnt(11)
	v_mfma_f32_16x16x32_bf16 v[190:193], v[56:59], v[12:15], 0
	v_mfma_f32_16x16x32_bf16 v[190:193], v[60:63], v[8:11], v[190:193]
	v_mfma_f32_16x16x32_bf16 v[190:193], v[64:67], v[4:7], v[190:193]
	v_mfma_f32_16x16x32_bf16 v[190:193], v[68:71], v[0:3], v[190:193]
	ds_read_b128 v[56:59], v241 offset:21952
	s_add_u32 s2, s0, 0x6000
	s_addc_u32 s3, s1, 0
	ds_read_b128 v[60:63], v241 offset:26112
	ds_read_b128 v[64:67], v241 offset:26176
	ds_read_b128 v[68:71], v241 offset:26240
	s_nop 7
	s_nop 3
	v_ashrrev_i32_e32 v197, 31, v198
	v_or_b32_e32 v197, 0x80000000, v197
	v_xor_b32_e32 v197, v198, v197
	v_and_or_b32 v151, v197, s80, v90
	v_ashrrev_i32_e32 v202, 31, v199
	v_or_b32_e32 v202, 0x80000000, v202
	v_xor_b32_e32 v202, v199, v202
	v_and_or_b32 v152, v202, s80, v116
	v_ashrrev_i32_e32 v197, 31, v200
	v_or_b32_e32 v197, 0x80000000, v197
	v_xor_b32_e32 v197, v200, v197
	v_and_or_b32 v153, v197, s80, v117
	v_ashrrev_i32_e32 v202, 31, v201
	v_or_b32_e32 v202, 0x80000000, v202
	v_xor_b32_e32 v202, v201, v202
	v_and_or_b32 v154, v202, s80, v118
	s_waitcnt lgkmcnt(11)
	v_mfma_f32_16x16x32_bf16 v[198:201], v[72:75], v[12:15], 0
	v_mfma_f32_16x16x32_bf16 v[198:201], v[76:79], v[8:11], v[198:201]
	v_mfma_f32_16x16x32_bf16 v[198:201], v[80:83], v[4:7], v[198:201]
	v_mfma_f32_16x16x32_bf16 v[198:201], v[24:27], v[0:3], v[198:201]
	ds_read_b128 v[72:75], v241 offset:26304
	s_add_u32 s2, s0, 0x7000
	s_addc_u32 s3, s1, 0
	ds_read_b128 v[76:79], v241 offset:30464
	ds_read_b128 v[80:83], v241 offset:30528
	ds_read_b128 v[24:27], v241 offset:30592
	s_nop 7
	s_nop 3
	v_ashrrev_i32_e32 v197, 31, v190
	v_or_b32_e32 v197, 0x80000000, v197
	v_xor_b32_e32 v197, v190, v197
	v_and_or_b32 v155, v197, s80, v91
	v_ashrrev_i32_e32 v202, 31, v191
	v_or_b32_e32 v202, 0x80000000, v202
	v_xor_b32_e32 v202, v191, v202
	v_and_or_b32 v156, v202, s80, v119
	v_ashrrev_i32_e32 v197, 31, v192
	v_or_b32_e32 v197, 0x80000000, v197
	v_xor_b32_e32 v197, v192, v197
	v_and_or_b32 v157, v197, s80, v120
	v_ashrrev_i32_e32 v202, 31, v193
	v_or_b32_e32 v202, 0x80000000, v202
	v_xor_b32_e32 v202, v193, v202
	v_and_or_b32 v158, v202, s80, v121
	s_waitcnt lgkmcnt(11)
	v_mfma_f32_16x16x32_bf16 v[190:193], v[28:31], v[12:15], 0
	v_mfma_f32_16x16x32_bf16 v[190:193], v[32:35], v[8:11], v[190:193]
	v_mfma_f32_16x16x32_bf16 v[190:193], v[36:39], v[4:7], v[190:193]
	v_mfma_f32_16x16x32_bf16 v[190:193], v[40:43], v[0:3], v[190:193]
	ds_read_b128 v[28:31], v241 offset:30656
	s_nop 7
	s_nop 3
	v_ashrrev_i32_e32 v197, 31, v198
	v_or_b32_e32 v197, 0x80000000, v197
	v_xor_b32_e32 v197, v198, v197
	v_and_or_b32 v159, v197, s80, v92
	v_ashrrev_i32_e32 v202, 31, v199
	v_or_b32_e32 v202, 0x80000000, v202
	v_xor_b32_e32 v202, v199, v202
	v_and_or_b32 v160, v202, s80, v122
	v_ashrrev_i32_e32 v197, 31, v200
	v_or_b32_e32 v197, 0x80000000, v197
	v_xor_b32_e32 v197, v200, v197
	v_and_or_b32 v161, v197, s80, v123
	v_ashrrev_i32_e32 v202, 31, v201
	v_or_b32_e32 v202, 0x80000000, v202
	v_xor_b32_e32 v202, v201, v202
	v_and_or_b32 v162, v202, s80, v124
	s_waitcnt lgkmcnt(8)
; #define MFMA(a, b, c) __builtin_amdgcn_mfma_f32_16x16x32_bf16((a), (b), (c), 0, 0, 0)
; DI unsigned ordf(float f) { unsigned u = __float_as_uint(f); return (u & 0x80000000u) ? ~u : (u | 0x80000000u); }
; DI void peer_topk_wave(const Params& p, int item, unsigned* lds  ) {
;     ...
; #pragma unroll
;     for (int mt = 0; mt < 8; ++mt) {
;       f32x4 a = (f32x4){0.f, 0.f, 0.f, 0.f};
; #pragma unroll
;       for (int ks = 0; ks < 4; ++ks) {
;         bf16x8 kf = *(const bf16x8*)&sk[(mt * 16 + r) * 128 + ks * 32 + kg * 8];
;         a = MFMA(kf, qf[ks], a);
;       }
; #pragma unroll
;       for (int j = 0; j < 4; ++j) kk[mt * 4 + j] = (ordf(a[j]) & ~127u) | (unsigned)(mt * 16 + kg * 4 + j);
;     }
; #pragma unroll
;     for (int rr = 0; rr < 16; ++rr) {
;       unsigned m = 0;
; #pragma unroll
;       for (int i = 0; i < 32; ++i) m = umax(m, kk[i]);
;       m = umax(m, (unsigned)__shfl_xor((int)m, 16));
;       m = umax(m, (unsigned)__shfl_xor((int)m, 32));
;       win[pp][rr] = m;
; #pragma unroll
;       for (int i = 0; i < 32; ++i) kk[i] = (kk[i] == m) ? 0u : kk[i];
;     }
	v_mfma_f32_16x16x32_bf16 v[198:201], v[44:47], v[12:15], 0
	v_mfma_f32_16x16x32_bf16 v[198:201], v[48:51], v[8:11], v[198:201]
	v_mfma_f32_16x16x32_bf16 v[198:201], v[52:55], v[4:7], v[198:201]
	v_mfma_f32_16x16x32_bf16 v[198:201], v[56:59], v[0:3], v[198:201]
	s_nop 7
	s_nop 3
	v_ashrrev_i32_e32 v197, 31, v190
	v_or_b32_e32 v197, 0x80000000, v197
	v_xor_b32_e32 v197, v190, v197
	v_and_or_b32 v164, v197, s80, v93
	v_ashrrev_i32_e32 v202, 31, v191
	v_or_b32_e32 v202, 0x80000000, v202
	v_xor_b32_e32 v202, v191, v202
	v_and_or_b32 v165, v202, s80, v125
	v_ashrrev_i32_e32 v197, 31, v192
	v_or_b32_e32 v197, 0x80000000, v197
	v_xor_b32_e32 v197, v192, v197
	v_and_or_b32 v166, v197, s80, v126
	v_ashrrev_i32_e32 v202, 31, v193
	v_or_b32_e32 v202, 0x80000000, v202
	v_xor_b32_e32 v202, v193, v202
	v_and_or_b32 v167, v202, s80, v127
	s_waitcnt lgkmcnt(4)
	v_mfma_f32_16x16x32_bf16 v[190:193], v[60:63], v[12:15], 0
	v_mfma_f32_16x16x32_bf16 v[190:193], v[64:67], v[8:11], v[190:193]
	v_mfma_f32_16x16x32_bf16 v[190:193], v[68:71], v[4:7], v[190:193]
	v_mfma_f32_16x16x32_bf16 v[190:193], v[72:75], v[0:3], v[190:193]
	s_nop 7
	s_nop 3
	v_ashrrev_i32_e32 v197, 31, v198
	v_or_b32_e32 v197, 0x80000000, v197
	v_xor_b32_e32 v197, v198, v197
	v_and_or_b32 v168, v197, s80, v94
	v_ashrrev_i32_e32 v202, 31, v199
	v_or_b32_e32 v202, 0x80000000, v202
	v_xor_b32_e32 v202, v199, v202
	v_and_or_b32 v169, v202, s80, v129
	v_ashrrev_i32_e32 v197, 31, v200
	v_or_b32_e32 v197, 0x80000000, v197
	v_xor_b32_e32 v197, v200, v197
	v_and_or_b32 v171, v197, s80, v130
	v_ashrrev_i32_e32 v202, 31, v201
	v_or_b32_e32 v202, 0x80000000, v202
	v_xor_b32_e32 v202, v201, v202
	v_and_or_b32 v172, v202, s80, v131
	s_waitcnt lgkmcnt(0)
	v_mfma_f32_16x16x32_bf16 v[198:201], v[76:79], v[12:15], 0
	v_mfma_f32_16x16x32_bf16 v[198:201], v[80:83], v[8:11], v[198:201]
	v_mfma_f32_16x16x32_bf16 v[198:201], v[24:27], v[4:7], v[198:201]
	v_mfma_f32_16x16x32_bf16 v[198:201], v[28:31], v[0:3], v[198:201]
	s_nop 7
	s_nop 3
	v_ashrrev_i32_e32 v197, 31, v190
	v_or_b32_e32 v197, 0x80000000, v197
	v_xor_b32_e32 v197, v190, v197
	v_and_or_b32 v173, v197, s80, v95
	v_ashrrev_i32_e32 v202, 31, v191
	v_or_b32_e32 v202, 0x80000000, v202
	v_xor_b32_e32 v202, v191, v202
	v_and_or_b32 v180, v202, s80, v135
	v_ashrrev_i32_e32 v197, 31, v192
	v_or_b32_e32 v197, 0x80000000, v197
	v_xor_b32_e32 v197, v192, v197
	v_and_or_b32 v181, v197, s80, v136
	v_ashrrev_i32_e32 v202, 31, v193
	v_or_b32_e32 v202, 0x80000000, v202
	v_xor_b32_e32 v202, v193, v202
	v_and_or_b32 v182, v202, s80, v137
	s_nop 7
	s_nop 3
	v_ashrrev_i32_e32 v197, 31, v198
	v_or_b32_e32 v197, 0x80000000, v197
	v_xor_b32_e32 v197, v198, v197
	v_and_or_b32 v0, v197, s80, v96
	v_ashrrev_i32_e32 v202, 31, v199
	v_or_b32_e32 v202, 0x80000000, v202
	v_xor_b32_e32 v202, v199, v202
	v_and_or_b32 v1, v202, s80, v138
	v_ashrrev_i32_e32 v197, 31, v200
	v_or_b32_e32 v197, 0x80000000, v197
	v_xor_b32_e32 v197, v200, v197
	v_and_or_b32 v2, v197, s80, v139
	v_ashrrev_i32_e32 v202, 31, v201
	v_or_b32_e32 v202, 0x80000000, v202
	v_xor_b32_e32 v202, v201, v202
	v_and_or_b32 v3, v202, s80, v140
	v_max_u32_e32 v24, v147, v148
	v_max3_u32 v24, v24, v149, v150
	v_max3_u32 v24, v24, v151, v152
	v_max3_u32 v24, v24, v153, v154
	v_max3_u32 v24, v24, v155, v156
	v_max3_u32 v24, v24, v157, v158
	v_max3_u32 v24, v24, v159, v160
	v_max3_u32 v24, v24, v161, v162
	v_max3_u32 v24, v24, v164, v165
	v_max3_u32 v24, v24, v166, v167
	v_max3_u32 v24, v24, v168, v169
	v_max3_u32 v24, v24, v171, v172
	v_max3_u32 v24, v24, v173, v180
	v_max3_u32 v24, v24, v181, v182
	v_max3_u32 v24, v24, v0, v1
	v_max3_u32 v24, v24, v2, v3
	v_mov_b32_e32 v25, v24
	s_nop 1
	v_permlane16_swap_b32 v24, v25
	s_nop 1
	v_max_u32_e32 v24, v24, v25
	v_mov_b32_e32 v25, v24
	s_nop 1
	v_permlane32_swap_b32 v24, v25
	s_nop 1
	v_max_u32_e32 v40, v24, v25
	v_sub_u32_e32 v26, v147, v40
	v_sub_u32_e32 v27, v148, v40
	v_max_u32_e32 v24, v26, v27
	v_sub_u32_e32 v28, v149, v40
	v_sub_u32_e32 v29, v150, v40
	v_max3_u32 v24, v24, v28, v29
	v_sub_u32_e32 v30, v151, v40
	v_sub_u32_e32 v31, v152, v40
	v_max3_u32 v24, v24, v30, v31
	v_sub_u32_e32 v32, v153, v40
	v_sub_u32_e32 v33, v154, v40
	v_max3_u32 v24, v24, v32, v33
	v_sub_u32_e32 v26, v155, v40
	v_sub_u32_e32 v27, v156, v40
	v_max3_u32 v24, v24, v26, v27
	v_sub_u32_e32 v28, v157, v40
	v_sub_u32_e32 v29, v158, v40
	v_max3_u32 v24, v24, v28, v29
	v_sub_u32_e32 v30, v159, v40
	v_sub_u32_e32 v31, v160, v40
	v_max3_u32 v24, v24, v30, v31
	v_sub_u32_e32 v32, v161, v40
	v_sub_u32_e32 v33, v162, v40
	v_max3_u32 v24, v24, v32, v33
	v_sub_u32_e32 v26, v164, v40
	v_sub_u32_e32 v27, v165, v40
	v_max3_u32 v24, v24, v26, v27
	v_sub_u32_e32 v28, v166, v40
	v_sub_u32_e32 v29, v167, v40
	v_max3_u32 v24, v24, v28, v29
	v_sub_u32_e32 v30, v168, v40
	v_sub_u32_e32 v31, v169, v40
	v_max3_u32 v24, v24, v30, v31
	v_sub_u32_e32 v32, v171, v40
	v_sub_u32_e32 v33, v172, v40
	v_max3_u32 v24, v24, v32, v33
	v_sub_u32_e32 v26, v173, v40
	v_sub_u32_e32 v27, v180, v40
	v_max3_u32 v24, v24, v26, v27
	v_sub_u32_e32 v28, v181, v40
	v_sub_u32_e32 v29, v182, v40
	v_max3_u32 v24, v24, v28, v29
	v_sub_u32_e32 v30, v0, v40
	v_sub_u32_e32 v31, v1, v40
	v_max3_u32 v24, v24, v30, v31
	v_sub_u32_e32 v32, v2, v40
	v_sub_u32_e32 v33, v3, v40
	v_max3_u32 v24, v24, v32, v33
	v_mov_b32_e32 v25, v24
	s_nop 1
	v_permlane16_swap_b32 v24, v25
	s_nop 1
	v_max_u32_e32 v24, v24, v25
	v_mov_b32_e32 v25, v24
	s_nop 1
	v_permlane32_swap_b32 v24, v25
	s_nop 1
	v_max_u32_e32 v24, v24, v25
	v_add_u32_e32 v41, v24, v40
	v_sub_u32_e32 v26, v147, v41
	v_sub_u32_e32 v27, v148, v41
	v_max_u32_e32 v24, v26, v27
	v_sub_u32_e32 v28, v149, v41
; DI void peer_topk_wave(const Params& p, int item, unsigned* lds  ) {
;     ...
;     for (int rr = 0; rr < 16; ++rr) {
;       unsigned m = 0;
; #pragma unroll
;       for (int i = 0; i < 32; ++i) m = umax(m, kk[i]);
;       m = umax(m, (unsigned)__shfl_xor((int)m, 16));
;       m = umax(m, (unsigned)__shfl_xor((int)m, 32));
;       win[pp][rr] = m;
; #pragma unroll
;       for (int i = 0; i < 32; ++i) kk[i] = (kk[i] == m) ? 0u : kk[i];
	v_sub_u32_e32 v29, v150, v41
	v_max3_u32 v24, v24, v28, v29
	v_sub_u32_e32 v30, v151, v41
	v_sub_u32_e32 v31, v152, v41
	v_max3_u32 v24, v24, v30, v31
	v_sub_u32_e32 v32, v153, v41
	v_sub_u32_e32 v33, v154, v41
	v_max3_u32 v24, v24, v32, v33
	v_sub_u32_e32 v26, v155, v41
	v_sub_u32_e32 v27, v156, v41
	v_max3_u32 v24, v24, v26, v27
	v_sub_u32_e32 v28, v157, v41
	v_sub_u32_e32 v29, v158, v41
	v_max3_u32 v24, v24, v28, v29
	v_sub_u32_e32 v30, v159, v41
	v_sub_u32_e32 v31, v160, v41
	v_max3_u32 v24, v24, v30, v31
	v_sub_u32_e32 v32, v161, v41
	v_sub_u32_e32 v33, v162, v41
	v_max3_u32 v24, v24, v32, v33
	v_sub_u32_e32 v26, v164, v41
	v_sub_u32_e32 v27, v165, v41
	v_max3_u32 v24, v24, v26, v27
	v_sub_u32_e32 v28, v166, v41
	v_sub_u32_e32 v29, v167, v41
	v_max3_u32 v24, v24, v28, v29
	v_sub_u32_e32 v30, v168, v41
	v_sub_u32_e32 v31, v169, v41
	v_max3_u32 v24, v24, v30, v31
	v_sub_u32_e32 v32, v171, v41
	v_sub_u32_e32 v33, v172, v41
	v_max3_u32 v24, v24, v32, v33
	v_sub_u32_e32 v26, v173, v41
	v_sub_u32_e32 v27, v180, v41
	v_max3_u32 v24, v24, v26, v27
	v_sub_u32_e32 v28, v181, v41
	v_sub_u32_e32 v29, v182, v41
	v_max3_u32 v24, v24, v28, v29
	v_sub_u32_e32 v30, v0, v41
	v_sub_u32_e32 v31, v1, v41
	v_max3_u32 v24, v24, v30, v31
	v_sub_u32_e32 v32, v2, v41
	v_sub_u32_e32 v33, v3, v41
	v_max3_u32 v24, v24, v32, v33
	v_mov_b32_e32 v25, v24
	s_nop 1
	v_permlane16_swap_b32 v24, v25
	s_nop 1
	v_max_u32_e32 v24, v24, v25
	v_mov_b32_e32 v25, v24
	s_nop 1
	v_permlane32_swap_b32 v24, v25
	s_nop 1
	v_max_u32_e32 v24, v24, v25
	v_add_u32_e32 v42, v24, v41
	v_sub_u32_e32 v26, v147, v42
	v_sub_u32_e32 v27, v148, v42
	v_max_u32_e32 v24, v26, v27
	v_sub_u32_e32 v28, v149, v42
	v_sub_u32_e32 v29, v150, v42
	v_max3_u32 v24, v24, v28, v29
	v_sub_u32_e32 v30, v151, v42
	v_sub_u32_e32 v31, v152, v42
	v_max3_u32 v24, v24, v30, v31
	v_sub_u32_e32 v32, v153, v42
	v_sub_u32_e32 v33, v154, v42
	v_max3_u32 v24, v24, v32, v33
	v_sub_u32_e32 v26, v155, v42
	v_sub_u32_e32 v27, v156, v42
	v_max3_u32 v24, v24, v26, v27
	v_sub_u32_e32 v28, v157, v42
	v_sub_u32_e32 v29, v158, v42
	v_max3_u32 v24, v24, v28, v29
	v_sub_u32_e32 v30, v159, v42
	v_sub_u32_e32 v31, v160, v42
	v_max3_u32 v24, v24, v30, v31
	v_sub_u32_e32 v32, v161, v42
	v_sub_u32_e32 v33, v162, v42
	v_max3_u32 v24, v24, v32, v33
	v_sub_u32_e32 v26, v164, v42
	v_sub_u32_e32 v27, v165, v42
	v_max3_u32 v24, v24, v26, v27
	v_sub_u32_e32 v28, v166, v42
	v_sub_u32_e32 v29, v167, v42
	v_max3_u32 v24, v24, v28, v29
	v_sub_u32_e32 v30, v168, v42
	v_sub_u32_e32 v31, v169, v42
	v_max3_u32 v24, v24, v30, v31
	v_sub_u32_e32 v32, v171, v42
	v_sub_u32_e32 v33, v172, v42
	v_max3_u32 v24, v24, v32, v33
	v_sub_u32_e32 v26, v173, v42
	v_sub_u32_e32 v27, v180, v42
	v_max3_u32 v24, v24, v26, v27
	v_sub_u32_e32 v28, v181, v42
	v_sub_u32_e32 v29, v182, v42
	v_max3_u32 v24, v24, v28, v29
	v_sub_u32_e32 v30, v0, v42
	v_sub_u32_e32 v31, v1, v42
	v_max3_u32 v24, v24, v30, v31
	v_sub_u32_e32 v32, v2, v42
	v_sub_u32_e32 v33, v3, v42
	v_max3_u32 v24, v24, v32, v33
	v_mov_b32_e32 v25, v24
	s_nop 1
	v_permlane16_swap_b32 v24, v25
	s_nop 1
	v_max_u32_e32 v24, v24, v25
	v_mov_b32_e32 v25, v24
	s_nop 1
	v_permlane32_swap_b32 v24, v25
	s_nop 1
	v_max_u32_e32 v24, v24, v25
	v_add_u32_e32 v43, v24, v42
	v_sub_u32_e32 v26, v147, v43
	v_sub_u32_e32 v27, v148, v43
	v_max_u32_e32 v24, v26, v27
	v_sub_u32_e32 v28, v149, v43
	v_sub_u32_e32 v29, v150, v43
	v_max3_u32 v24, v24, v28, v29
	v_sub_u32_e32 v30, v151, v43
	v_sub_u32_e32 v31, v152, v43
	v_max3_u32 v24, v24, v30, v31
	v_sub_u32_e32 v32, v153, v43
	v_sub_u32_e32 v33, v154, v43
	v_max3_u32 v24, v24, v32, v33
	v_sub_u32_e32 v26, v155, v43
	v_sub_u32_e32 v27, v156, v43
	v_max3_u32 v24, v24, v26, v27
	v_sub_u32_e32 v28, v157, v43
	v_sub_u32_e32 v29, v158, v43
	v_max3_u32 v24, v24, v28, v29
	v_sub_u32_e32 v30, v159, v43
	v_sub_u32_e32 v31, v160, v43
	v_max3_u32 v24, v24, v30, v31
	v_sub_u32_e32 v32, v161, v43
	v_sub_u32_e32 v33, v162, v43
	v_max3_u32 v24, v24, v32, v33
	v_sub_u32_e32 v26, v164, v43
	v_sub_u32_e32 v27, v165, v43
	v_max3_u32 v24, v24, v26, v27
	v_sub_u32_e32 v28, v166, v43
	v_sub_u32_e32 v29, v167, v43
	v_max3_u32 v24, v24, v28, v29
	v_sub_u32_e32 v30, v168, v43
	v_sub_u32_e32 v31, v169, v43
	v_max3_u32 v24, v24, v30, v31
	v_sub_u32_e32 v32, v171, v43
	v_sub_u32_e32 v33, v172, v43
	v_max3_u32 v24, v24, v32, v33
	v_sub_u32_e32 v26, v173, v43
	v_sub_u32_e32 v27, v180, v43
	v_max3_u32 v24, v24, v26, v27
	v_sub_u32_e32 v28, v181, v43
	v_sub_u32_e32 v29, v182, v43
	v_max3_u32 v24, v24, v28, v29
	v_sub_u32_e32 v30, v0, v43
	v_sub_u32_e32 v31, v1, v43
	v_max3_u32 v24, v24, v30, v31
	v_sub_u32_e32 v32, v2, v43
	v_sub_u32_e32 v33, v3, v43
	v_max3_u32 v24, v24, v32, v33
	v_mov_b32_e32 v25, v24
	s_nop 1
	v_permlane16_swap_b32 v24, v25
	s_nop 1
	v_max_u32_e32 v24, v24, v25
	v_mov_b32_e32 v25, v24
	s_nop 1
	v_permlane32_swap_b32 v24, v25
	s_nop 1
	v_max_u32_e32 v24, v24, v25
	v_add_u32_e32 v44, v24, v43
	v_sub_u32_e32 v26, v147, v44
	v_sub_u32_e32 v27, v148, v44
	v_max_u32_e32 v24, v26, v27
	v_sub_u32_e32 v28, v149, v44
	v_sub_u32_e32 v29, v150, v44
	v_max3_u32 v24, v24, v28, v29
	v_sub_u32_e32 v30, v151, v44
	v_sub_u32_e32 v31, v152, v44
	v_max3_u32 v24, v24, v30, v31
	v_sub_u32_e32 v32, v153, v44
	v_sub_u32_e32 v33, v154, v44
	v_max3_u32 v24, v24, v32, v33
	v_sub_u32_e32 v26, v155, v44
	v_sub_u32_e32 v27, v156, v44
	v_max3_u32 v24, v24, v26, v27
	v_sub_u32_e32 v28, v157, v44
	v_sub_u32_e32 v29, v158, v44
	v_max3_u32 v24, v24, v28, v29
	v_sub_u32_e32 v30, v159, v44
	v_sub_u32_e32 v31, v160, v44
	v_max3_u32 v24, v24, v30, v31
	v_sub_u32_e32 v32, v161, v44
	v_sub_u32_e32 v33, v162, v44
	v_max3_u32 v24, v24, v32, v33
; DI void peer_topk_wave(const Params& p, int item, unsigned* lds  ) {
;     ...
;     for (int rr = 0; rr < 16; ++rr) {
;       unsigned m = 0;
; #pragma unroll
;       for (int i = 0; i < 32; ++i) m = umax(m, kk[i]);
;       m = umax(m, (unsigned)__shfl_xor((int)m, 16));
;       m = umax(m, (unsigned)__shfl_xor((int)m, 32));
;       win[pp][rr] = m;
; #pragma unroll
;       for (int i = 0; i < 32; ++i) kk[i] = (kk[i] == m) ? 0u : kk[i];
	v_sub_u32_e32 v26, v164, v44
	v_sub_u32_e32 v27, v165, v44
	v_max3_u32 v24, v24, v26, v27
	v_sub_u32_e32 v28, v166, v44
	v_sub_u32_e32 v29, v167, v44
	v_max3_u32 v24, v24, v28, v29
	v_sub_u32_e32 v30, v168, v44
	v_sub_u32_e32 v31, v169, v44
	v_max3_u32 v24, v24, v30, v31
	v_sub_u32_e32 v32, v171, v44
	v_sub_u32_e32 v33, v172, v44
	v_max3_u32 v24, v24, v32, v33
	v_sub_u32_e32 v26, v173, v44
	v_sub_u32_e32 v27, v180, v44
	v_max3_u32 v24, v24, v26, v27
	v_sub_u32_e32 v28, v181, v44
	v_sub_u32_e32 v29, v182, v44
	v_max3_u32 v24, v24, v28, v29
	v_sub_u32_e32 v30, v0, v44
	v_sub_u32_e32 v31, v1, v44
	v_max3_u32 v24, v24, v30, v31
	v_sub_u32_e32 v32, v2, v44
	v_sub_u32_e32 v33, v3, v44
	v_max3_u32 v24, v24, v32, v33
	v_mov_b32_e32 v25, v24
	s_nop 1
	v_permlane16_swap_b32 v24, v25
	s_nop 1
	v_max_u32_e32 v24, v24, v25
	v_mov_b32_e32 v25, v24
	s_nop 1
	v_permlane32_swap_b32 v24, v25
	s_nop 1
	v_max_u32_e32 v24, v24, v25
	v_add_u32_e32 v45, v24, v44
	v_sub_u32_e32 v26, v147, v45
	v_sub_u32_e32 v27, v148, v45
	v_max_u32_e32 v24, v26, v27
	v_sub_u32_e32 v28, v149, v45
	v_sub_u32_e32 v29, v150, v45
	v_max3_u32 v24, v24, v28, v29
	v_sub_u32_e32 v30, v151, v45
	v_sub_u32_e32 v31, v152, v45
	v_max3_u32 v24, v24, v30, v31
	v_sub_u32_e32 v32, v153, v45
	v_sub_u32_e32 v33, v154, v45
	v_max3_u32 v24, v24, v32, v33
	v_sub_u32_e32 v26, v155, v45
	v_sub_u32_e32 v27, v156, v45
	v_max3_u32 v24, v24, v26, v27
	v_sub_u32_e32 v28, v157, v45
	v_sub_u32_e32 v29, v158, v45
	v_max3_u32 v24, v24, v28, v29
	v_sub_u32_e32 v30, v159, v45
	v_sub_u32_e32 v31, v160, v45
	v_max3_u32 v24, v24, v30, v31
	v_sub_u32_e32 v32, v161, v45
	v_sub_u32_e32 v33, v162, v45
	v_max3_u32 v24, v24, v32, v33
	v_sub_u32_e32 v26, v164, v45
	v_sub_u32_e32 v27, v165, v45
	v_max3_u32 v24, v24, v26, v27
	v_sub_u32_e32 v28, v166, v45
	v_sub_u32_e32 v29, v167, v45
	v_max3_u32 v24, v24, v28, v29
	v_sub_u32_e32 v30, v168, v45
	v_sub_u32_e32 v31, v169, v45
	v_max3_u32 v24, v24, v30, v31
	v_sub_u32_e32 v32, v171, v45
	v_sub_u32_e32 v33, v172, v45
	v_max3_u32 v24, v24, v32, v33
	v_sub_u32_e32 v26, v173, v45
	v_sub_u32_e32 v27, v180, v45
	v_max3_u32 v24, v24, v26, v27
	v_sub_u32_e32 v28, v181, v45
	v_sub_u32_e32 v29, v182, v45
	v_max3_u32 v24, v24, v28, v29
	v_sub_u32_e32 v30, v0, v45
	v_sub_u32_e32 v31, v1, v45
	v_max3_u32 v24, v24, v30, v31
	v_sub_u32_e32 v32, v2, v45
	v_sub_u32_e32 v33, v3, v45
	v_max3_u32 v24, v24, v32, v33
	v_mov_b32_e32 v25, v24
	s_nop 1
	v_permlane16_swap_b32 v24, v25
	s_nop 1
	v_max_u32_e32 v24, v24, v25
	v_mov_b32_e32 v25, v24
	s_nop 1
	v_permlane32_swap_b32 v24, v25
	s_nop 1
	v_max_u32_e32 v24, v24, v25
	v_add_u32_e32 v46, v24, v45
	v_sub_u32_e32 v26, v147, v46
	v_sub_u32_e32 v27, v148, v46
	v_max_u32_e32 v24, v26, v27
	v_sub_u32_e32 v28, v149, v46
	v_sub_u32_e32 v29, v150, v46
	v_max3_u32 v24, v24, v28, v29
	v_sub_u32_e32 v30, v151, v46
	v_sub_u32_e32 v31, v152, v46
	v_max3_u32 v24, v24, v30, v31
	v_sub_u32_e32 v32, v153, v46
	v_sub_u32_e32 v33, v154, v46
	v_max3_u32 v24, v24, v32, v33
	v_sub_u32_e32 v26, v155, v46
	v_sub_u32_e32 v27, v156, v46
	v_max3_u32 v24, v24, v26, v27
	v_sub_u32_e32 v28, v157, v46
	v_sub_u32_e32 v29, v158, v46
	v_max3_u32 v24, v24, v28, v29
	v_sub_u32_e32 v30, v159, v46
	v_sub_u32_e32 v31, v160, v46
	v_max3_u32 v24, v24, v30, v31
	v_sub_u32_e32 v32, v161, v46
	v_sub_u32_e32 v33, v162, v46
	v_max3_u32 v24, v24, v32, v33
	v_sub_u32_e32 v26, v164, v46
	v_sub_u32_e32 v27, v165, v46
	v_max3_u32 v24, v24, v26, v27
	v_sub_u32_e32 v28, v166, v46
	v_sub_u32_e32 v29, v167, v46
	v_max3_u32 v24, v24, v28, v29
	v_sub_u32_e32 v30, v168, v46
	v_sub_u32_e32 v31, v169, v46
	v_max3_u32 v24, v24, v30, v31
	v_sub_u32_e32 v32, v171, v46
	v_sub_u32_e32 v33, v172, v46
	v_max3_u32 v24, v24, v32, v33
	v_sub_u32_e32 v26, v173, v46
	v_sub_u32_e32 v27, v180, v46
	v_max3_u32 v24, v24, v26, v27
	v_sub_u32_e32 v28, v181, v46
	v_sub_u32_e32 v29, v182, v46
	v_max3_u32 v24, v24, v28, v29
	v_sub_u32_e32 v30, v0, v46
	v_sub_u32_e32 v31, v1, v46
	v_max3_u32 v24, v24, v30, v31
	v_sub_u32_e32 v32, v2, v46
	v_sub_u32_e32 v33, v3, v46
	v_max3_u32 v24, v24, v32, v33
	v_mov_b32_e32 v25, v24
	s_nop 1
	v_permlane16_swap_b32 v24, v25
	s_nop 1
	v_max_u32_e32 v24, v24, v25
	v_mov_b32_e32 v25, v24
	s_nop 1
	v_permlane32_swap_b32 v24, v25
	s_nop 1
	v_max_u32_e32 v24, v24, v25
	v_add_u32_e32 v47, v24, v46
	v_sub_u32_e32 v26, v147, v47
	v_sub_u32_e32 v27, v148, v47
	v_max_u32_e32 v24, v26, v27
	v_sub_u32_e32 v28, v149, v47
	v_sub_u32_e32 v29, v150, v47
	v_max3_u32 v24, v24, v28, v29
	v_sub_u32_e32 v30, v151, v47
	v_sub_u32_e32 v31, v152, v47
	v_max3_u32 v24, v24, v30, v31
	v_sub_u32_e32 v32, v153, v47
	v_sub_u32_e32 v33, v154, v47
	v_max3_u32 v24, v24, v32, v33
	v_sub_u32_e32 v26, v155, v47
	v_sub_u32_e32 v27, v156, v47
	v_max3_u32 v24, v24, v26, v27
	v_sub_u32_e32 v28, v157, v47
	v_sub_u32_e32 v29, v158, v47
	v_max3_u32 v24, v24, v28, v29
	v_sub_u32_e32 v30, v159, v47
	v_sub_u32_e32 v31, v160, v47
	v_max3_u32 v24, v24, v30, v31
	v_sub_u32_e32 v32, v161, v47
	v_sub_u32_e32 v33, v162, v47
	v_max3_u32 v24, v24, v32, v33
	v_sub_u32_e32 v26, v164, v47
	v_sub_u32_e32 v27, v165, v47
	v_max3_u32 v24, v24, v26, v27
	v_sub_u32_e32 v28, v166, v47
	v_sub_u32_e32 v29, v167, v47
	v_max3_u32 v24, v24, v28, v29
	v_sub_u32_e32 v30, v168, v47
	v_sub_u32_e32 v31, v169, v47
	v_max3_u32 v24, v24, v30, v31
	v_sub_u32_e32 v32, v171, v47
	v_sub_u32_e32 v33, v172, v47
	v_max3_u32 v24, v24, v32, v33
	v_sub_u32_e32 v26, v173, v47
	v_sub_u32_e32 v27, v180, v47
	v_max3_u32 v24, v24, v26, v27
	v_sub_u32_e32 v28, v181, v47
	v_sub_u32_e32 v29, v182, v47
	v_max3_u32 v24, v24, v28, v29
	v_sub_u32_e32 v30, v0, v47
	v_sub_u32_e32 v31, v1, v47
; DI void peer_topk_wave(const Params& p, int item, unsigned* lds  ) {
;     ...
;     for (int rr = 0; rr < 16; ++rr) {
;       unsigned m = 0;
; #pragma unroll
;       for (int i = 0; i < 32; ++i) m = umax(m, kk[i]);
;       m = umax(m, (unsigned)__shfl_xor((int)m, 16));
;       m = umax(m, (unsigned)__shfl_xor((int)m, 32));
;       win[pp][rr] = m;
; #pragma unroll
;       for (int i = 0; i < 32; ++i) kk[i] = (kk[i] == m) ? 0u : kk[i];
	v_max3_u32 v24, v24, v30, v31
	v_sub_u32_e32 v32, v2, v47
	v_sub_u32_e32 v33, v3, v47
	v_max3_u32 v24, v24, v32, v33
	v_mov_b32_e32 v25, v24
	s_nop 1
	v_permlane16_swap_b32 v24, v25
	s_nop 1
	v_max_u32_e32 v24, v24, v25
	v_mov_b32_e32 v25, v24
	s_nop 1
	v_permlane32_swap_b32 v24, v25
	s_nop 1
	v_max_u32_e32 v24, v24, v25
	v_add_u32_e32 v48, v24, v47
	v_sub_u32_e32 v26, v147, v48
	v_sub_u32_e32 v27, v148, v48
	v_max_u32_e32 v24, v26, v27
	v_sub_u32_e32 v28, v149, v48
	v_sub_u32_e32 v29, v150, v48
	v_max3_u32 v24, v24, v28, v29
	v_sub_u32_e32 v30, v151, v48
	v_sub_u32_e32 v31, v152, v48
	v_max3_u32 v24, v24, v30, v31
	v_sub_u32_e32 v32, v153, v48
	v_sub_u32_e32 v33, v154, v48
	v_max3_u32 v24, v24, v32, v33
	v_sub_u32_e32 v26, v155, v48
	v_sub_u32_e32 v27, v156, v48
	v_max3_u32 v24, v24, v26, v27
	v_sub_u32_e32 v28, v157, v48
	v_sub_u32_e32 v29, v158, v48
	v_max3_u32 v24, v24, v28, v29
	v_sub_u32_e32 v30, v159, v48
	v_sub_u32_e32 v31, v160, v48
	v_max3_u32 v24, v24, v30, v31
	v_sub_u32_e32 v32, v161, v48
	v_sub_u32_e32 v33, v162, v48
	v_max3_u32 v24, v24, v32, v33
	v_sub_u32_e32 v26, v164, v48
	v_sub_u32_e32 v27, v165, v48
	v_max3_u32 v24, v24, v26, v27
	v_sub_u32_e32 v28, v166, v48
	v_sub_u32_e32 v29, v167, v48
	v_max3_u32 v24, v24, v28, v29
	v_sub_u32_e32 v30, v168, v48
	v_sub_u32_e32 v31, v169, v48
	v_max3_u32 v24, v24, v30, v31
	v_sub_u32_e32 v32, v171, v48
	v_sub_u32_e32 v33, v172, v48
	v_max3_u32 v24, v24, v32, v33
	v_sub_u32_e32 v26, v173, v48
	v_sub_u32_e32 v27, v180, v48
	v_max3_u32 v24, v24, v26, v27
	v_sub_u32_e32 v28, v181, v48
	v_sub_u32_e32 v29, v182, v48
	v_max3_u32 v24, v24, v28, v29
	v_sub_u32_e32 v30, v0, v48
	v_sub_u32_e32 v31, v1, v48
	v_max3_u32 v24, v24, v30, v31
	v_sub_u32_e32 v32, v2, v48
	v_sub_u32_e32 v33, v3, v48
	v_max3_u32 v24, v24, v32, v33
	v_mov_b32_e32 v25, v24
	s_nop 1
	v_permlane16_swap_b32 v24, v25
	s_nop 1
	v_max_u32_e32 v24, v24, v25
	v_mov_b32_e32 v25, v24
	s_nop 1
	v_permlane32_swap_b32 v24, v25
	s_nop 1
	v_max_u32_e32 v24, v24, v25
	v_add_u32_e32 v49, v24, v48
	v_sub_u32_e32 v26, v147, v49
	v_sub_u32_e32 v27, v148, v49
	v_max_u32_e32 v24, v26, v27
	v_sub_u32_e32 v28, v149, v49
	v_sub_u32_e32 v29, v150, v49
	v_max3_u32 v24, v24, v28, v29
	v_sub_u32_e32 v30, v151, v49
	v_sub_u32_e32 v31, v152, v49
	v_max3_u32 v24, v24, v30, v31
	v_sub_u32_e32 v32, v153, v49
	v_sub_u32_e32 v33, v154, v49
	v_max3_u32 v24, v24, v32, v33
	v_sub_u32_e32 v26, v155, v49
	v_sub_u32_e32 v27, v156, v49
	v_max3_u32 v24, v24, v26, v27
	v_sub_u32_e32 v28, v157, v49
	v_sub_u32_e32 v29, v158, v49
	v_max3_u32 v24, v24, v28, v29
	v_sub_u32_e32 v30, v159, v49
	v_sub_u32_e32 v31, v160, v49
	v_max3_u32 v24, v24, v30, v31
	v_sub_u32_e32 v32, v161, v49
	v_sub_u32_e32 v33, v162, v49
	v_max3_u32 v24, v24, v32, v33
	v_sub_u32_e32 v26, v164, v49
	v_sub_u32_e32 v27, v165, v49
	v_max3_u32 v24, v24, v26, v27
	v_sub_u32_e32 v28, v166, v49
	v_sub_u32_e32 v29, v167, v49
	v_max3_u32 v24, v24, v28, v29
	v_sub_u32_e32 v30, v168, v49
	v_sub_u32_e32 v31, v169, v49
	v_max3_u32 v24, v24, v30, v31
	v_sub_u32_e32 v32, v171, v49
	v_sub_u32_e32 v33, v172, v49
	v_max3_u32 v24, v24, v32, v33
	v_sub_u32_e32 v26, v173, v49
	v_sub_u32_e32 v27, v180, v49
	v_max3_u32 v24, v24, v26, v27
	v_sub_u32_e32 v28, v181, v49
	v_sub_u32_e32 v29, v182, v49
	v_max3_u32 v24, v24, v28, v29
	v_sub_u32_e32 v30, v0, v49
	v_sub_u32_e32 v31, v1, v49
	v_max3_u32 v24, v24, v30, v31
	v_sub_u32_e32 v32, v2, v49
	v_sub_u32_e32 v33, v3, v49
	v_max3_u32 v24, v24, v32, v33
	v_mov_b32_e32 v25, v24
	s_nop 1
	v_permlane16_swap_b32 v24, v25
	s_nop 1
	v_max_u32_e32 v24, v24, v25
	v_mov_b32_e32 v25, v24
	s_nop 1
	v_permlane32_swap_b32 v24, v25
	s_nop 1
	v_max_u32_e32 v24, v24, v25
	v_add_u32_e32 v50, v24, v49
	v_sub_u32_e32 v26, v147, v50
	v_sub_u32_e32 v27, v148, v50
	v_max_u32_e32 v24, v26, v27
	v_sub_u32_e32 v28, v149, v50
	v_sub_u32_e32 v29, v150, v50
	v_max3_u32 v24, v24, v28, v29
	v_sub_u32_e32 v30, v151, v50
	v_sub_u32_e32 v31, v152, v50
	v_max3_u32 v24, v24, v30, v31
	v_sub_u32_e32 v32, v153, v50
	v_sub_u32_e32 v33, v154, v50
	v_max3_u32 v24, v24, v32, v33
	v_sub_u32_e32 v26, v155, v50
	v_sub_u32_e32 v27, v156, v50
	v_max3_u32 v24, v24, v26, v27
	v_sub_u32_e32 v28, v157, v50
	v_sub_u32_e32 v29, v158, v50
	v_max3_u32 v24, v24, v28, v29
	v_sub_u32_e32 v30, v159, v50
	v_sub_u32_e32 v31, v160, v50
	v_max3_u32 v24, v24, v30, v31
	v_sub_u32_e32 v32, v161, v50
	v_sub_u32_e32 v33, v162, v50
	v_max3_u32 v24, v24, v32, v33
	v_sub_u32_e32 v26, v164, v50
	v_sub_u32_e32 v27, v165, v50
	v_max3_u32 v24, v24, v26, v27
	v_sub_u32_e32 v28, v166, v50
	v_sub_u32_e32 v29, v167, v50
	v_max3_u32 v24, v24, v28, v29
	v_sub_u32_e32 v30, v168, v50
	v_sub_u32_e32 v31, v169, v50
	v_max3_u32 v24, v24, v30, v31
	v_sub_u32_e32 v32, v171, v50
	v_sub_u32_e32 v33, v172, v50
	v_max3_u32 v24, v24, v32, v33
	v_sub_u32_e32 v26, v173, v50
	v_sub_u32_e32 v27, v180, v50
	v_max3_u32 v24, v24, v26, v27
	v_sub_u32_e32 v28, v181, v50
	v_sub_u32_e32 v29, v182, v50
	v_max3_u32 v24, v24, v28, v29
	v_sub_u32_e32 v30, v0, v50
	v_sub_u32_e32 v31, v1, v50
	v_max3_u32 v24, v24, v30, v31
	v_sub_u32_e32 v32, v2, v50
	v_sub_u32_e32 v33, v3, v50
	v_max3_u32 v24, v24, v32, v33
	v_mov_b32_e32 v25, v24
	s_nop 1
	v_permlane16_swap_b32 v24, v25
	s_nop 1
	v_max_u32_e32 v24, v24, v25
	v_mov_b32_e32 v25, v24
	s_nop 1
	v_permlane32_swap_b32 v24, v25
	s_nop 1
	v_max_u32_e32 v24, v24, v25
	v_add_u32_e32 v51, v24, v50
	v_sub_u32_e32 v26, v147, v51
	v_sub_u32_e32 v27, v148, v51
	v_max_u32_e32 v24, v26, v27
	v_sub_u32_e32 v28, v149, v51
	v_sub_u32_e32 v29, v150, v51
	v_max3_u32 v24, v24, v28, v29
	v_sub_u32_e32 v30, v151, v51
	v_sub_u32_e32 v31, v152, v51
; DI void peer_topk_wave(const Params& p, int item, unsigned* lds  ) {
;     ...
;     for (int rr = 0; rr < 16; ++rr) {
;       unsigned m = 0;
; #pragma unroll
;       for (int i = 0; i < 32; ++i) m = umax(m, kk[i]);
;       m = umax(m, (unsigned)__shfl_xor((int)m, 16));
;       m = umax(m, (unsigned)__shfl_xor((int)m, 32));
;       win[pp][rr] = m;
; #pragma unroll
;       for (int i = 0; i < 32; ++i) kk[i] = (kk[i] == m) ? 0u : kk[i];
;     }
	v_max3_u32 v24, v24, v30, v31
	v_sub_u32_e32 v32, v153, v51
	v_sub_u32_e32 v33, v154, v51
	v_max3_u32 v24, v24, v32, v33
	v_sub_u32_e32 v26, v155, v51
	v_sub_u32_e32 v27, v156, v51
	v_max3_u32 v24, v24, v26, v27
	v_sub_u32_e32 v28, v157, v51
	v_sub_u32_e32 v29, v158, v51
	v_max3_u32 v24, v24, v28, v29
	v_sub_u32_e32 v30, v159, v51
	v_sub_u32_e32 v31, v160, v51
	v_max3_u32 v24, v24, v30, v31
	v_sub_u32_e32 v32, v161, v51
	v_sub_u32_e32 v33, v162, v51
	v_max3_u32 v24, v24, v32, v33
	v_sub_u32_e32 v26, v164, v51
	v_sub_u32_e32 v27, v165, v51
	v_max3_u32 v24, v24, v26, v27
	v_sub_u32_e32 v28, v166, v51
	v_sub_u32_e32 v29, v167, v51
	v_max3_u32 v24, v24, v28, v29
	v_sub_u32_e32 v30, v168, v51
	v_sub_u32_e32 v31, v169, v51
	v_max3_u32 v24, v24, v30, v31
	v_sub_u32_e32 v32, v171, v51
	v_sub_u32_e32 v33, v172, v51
	v_max3_u32 v24, v24, v32, v33
	v_sub_u32_e32 v26, v173, v51
	v_sub_u32_e32 v27, v180, v51
	v_max3_u32 v24, v24, v26, v27
	v_sub_u32_e32 v28, v181, v51
	v_sub_u32_e32 v29, v182, v51
	v_max3_u32 v24, v24, v28, v29
	v_sub_u32_e32 v30, v0, v51
	v_sub_u32_e32 v31, v1, v51
	v_max3_u32 v24, v24, v30, v31
	v_sub_u32_e32 v32, v2, v51
	v_sub_u32_e32 v33, v3, v51
	v_max3_u32 v24, v24, v32, v33
	v_mov_b32_e32 v25, v24
	s_nop 1
	v_permlane16_swap_b32 v24, v25
	s_nop 1
	v_max_u32_e32 v24, v24, v25
	v_mov_b32_e32 v25, v24
	s_nop 1
	v_permlane32_swap_b32 v24, v25
	s_nop 1
	v_max_u32_e32 v24, v24, v25
	v_add_u32_e32 v52, v24, v51
	v_sub_u32_e32 v26, v147, v52
	v_sub_u32_e32 v27, v148, v52
	v_max_u32_e32 v24, v26, v27
	v_sub_u32_e32 v28, v149, v52
	v_sub_u32_e32 v29, v150, v52
	v_max3_u32 v24, v24, v28, v29
	v_sub_u32_e32 v30, v151, v52
	v_sub_u32_e32 v31, v152, v52
	v_max3_u32 v24, v24, v30, v31
	v_sub_u32_e32 v32, v153, v52
	v_sub_u32_e32 v33, v154, v52
	v_max3_u32 v24, v24, v32, v33
	v_sub_u32_e32 v26, v155, v52
	v_sub_u32_e32 v27, v156, v52
	v_max3_u32 v24, v24, v26, v27
	v_sub_u32_e32 v28, v157, v52
	v_sub_u32_e32 v29, v158, v52
	v_max3_u32 v24, v24, v28, v29
	v_sub_u32_e32 v30, v159, v52
	v_sub_u32_e32 v31, v160, v52
	v_max3_u32 v24, v24, v30, v31
	v_sub_u32_e32 v32, v161, v52
	v_sub_u32_e32 v33, v162, v52
	v_max3_u32 v24, v24, v32, v33
	v_sub_u32_e32 v26, v164, v52
	v_sub_u32_e32 v27, v165, v52
	v_max3_u32 v24, v24, v26, v27
	v_sub_u32_e32 v28, v166, v52
	v_sub_u32_e32 v29, v167, v52
	v_max3_u32 v24, v24, v28, v29
	v_sub_u32_e32 v30, v168, v52
	v_sub_u32_e32 v31, v169, v52
	v_max3_u32 v24, v24, v30, v31
	v_sub_u32_e32 v32, v171, v52
	v_sub_u32_e32 v33, v172, v52
	v_max3_u32 v24, v24, v32, v33
	v_sub_u32_e32 v26, v173, v52
	v_sub_u32_e32 v27, v180, v52
	v_max3_u32 v24, v24, v26, v27
	v_sub_u32_e32 v28, v181, v52
	v_sub_u32_e32 v29, v182, v52
	v_max3_u32 v24, v24, v28, v29
	v_sub_u32_e32 v30, v0, v52
	v_sub_u32_e32 v31, v1, v52
	v_max3_u32 v24, v24, v30, v31
	v_sub_u32_e32 v32, v2, v52
	v_sub_u32_e32 v33, v3, v52
	v_max3_u32 v24, v24, v32, v33
	v_mov_b32_e32 v25, v24
	s_nop 1
	v_permlane16_swap_b32 v24, v25
	s_nop 1
	v_max_u32_e32 v24, v24, v25
	v_mov_b32_e32 v25, v24
	s_nop 1
	v_permlane32_swap_b32 v24, v25
	s_nop 1
	v_max_u32_e32 v24, v24, v25
	v_add_u32_e32 v53, v24, v52
	v_sub_u32_e32 v26, v147, v53
	v_sub_u32_e32 v27, v148, v53
	v_max_u32_e32 v24, v26, v27
	v_sub_u32_e32 v28, v149, v53
	v_sub_u32_e32 v29, v150, v53
	v_max3_u32 v24, v24, v28, v29
	v_sub_u32_e32 v30, v151, v53
	v_sub_u32_e32 v31, v152, v53
	v_max3_u32 v24, v24, v30, v31
	v_sub_u32_e32 v32, v153, v53
	v_sub_u32_e32 v33, v154, v53
	v_max3_u32 v24, v24, v32, v33
	v_sub_u32_e32 v26, v155, v53
	v_sub_u32_e32 v27, v156, v53
	v_max3_u32 v24, v24, v26, v27
	v_sub_u32_e32 v28, v157, v53
	v_sub_u32_e32 v29, v158, v53
	v_max3_u32 v24, v24, v28, v29
	v_sub_u32_e32 v30, v159, v53
	v_sub_u32_e32 v31, v160, v53
	v_max3_u32 v24, v24, v30, v31
	v_sub_u32_e32 v32, v161, v53
	v_sub_u32_e32 v33, v162, v53
	v_max3_u32 v24, v24, v32, v33
	v_sub_u32_e32 v26, v164, v53
	v_sub_u32_e32 v27, v165, v53
	v_max3_u32 v24, v24, v26, v27
	v_sub_u32_e32 v28, v166, v53
	v_sub_u32_e32 v29, v167, v53
	v_max3_u32 v24, v24, v28, v29
	v_sub_u32_e32 v30, v168, v53
	v_sub_u32_e32 v31, v169, v53
	v_max3_u32 v24, v24, v30, v31
	v_sub_u32_e32 v32, v171, v53
	v_sub_u32_e32 v33, v172, v53
	v_max3_u32 v24, v24, v32, v33
	v_sub_u32_e32 v26, v173, v53
	v_sub_u32_e32 v27, v180, v53
	v_max3_u32 v24, v24, v26, v27
	v_sub_u32_e32 v28, v181, v53
	v_sub_u32_e32 v29, v182, v53
	v_max3_u32 v24, v24, v28, v29
	v_sub_u32_e32 v30, v0, v53
	v_sub_u32_e32 v31, v1, v53
	v_max3_u32 v24, v24, v30, v31
	v_sub_u32_e32 v32, v2, v53
	v_sub_u32_e32 v33, v3, v53
	v_max3_u32 v24, v24, v32, v33
	v_mov_b32_e32 v25, v24
	s_nop 1
	v_permlane16_swap_b32 v24, v25
	s_nop 1
	v_max_u32_e32 v24, v24, v25
	v_mov_b32_e32 v25, v24
	s_nop 1
	v_permlane32_swap_b32 v24, v25
	s_nop 1
	v_max_u32_e32 v24, v24, v25
	v_add_u32_e32 v54, v24, v53
	v_sub_u32_e32 v26, v147, v54
	v_sub_u32_e32 v27, v148, v54
	v_max_u32_e32 v24, v26, v27
	v_sub_u32_e32 v28, v149, v54
	v_sub_u32_e32 v29, v150, v54
	v_max3_u32 v24, v24, v28, v29
	v_sub_u32_e32 v30, v151, v54
	v_sub_u32_e32 v31, v152, v54
	v_max3_u32 v24, v24, v30, v31
	v_sub_u32_e32 v32, v153, v54
	v_sub_u32_e32 v33, v154, v54
	v_max3_u32 v24, v24, v32, v33
	v_sub_u32_e32 v26, v155, v54
	v_sub_u32_e32 v27, v156, v54
	v_max3_u32 v24, v24, v26, v27
	v_sub_u32_e32 v28, v157, v54
	v_sub_u32_e32 v29, v158, v54
	v_max3_u32 v24, v24, v28, v29
	v_sub_u32_e32 v30, v159, v54
	v_sub_u32_e32 v31, v160, v54
	v_max3_u32 v24, v24, v30, v31
	v_sub_u32_e32 v32, v161, v54
	v_sub_u32_e32 v33, v162, v54
	v_max3_u32 v24, v24, v32, v33
	v_sub_u32_e32 v26, v164, v54
	v_sub_u32_e32 v27, v165, v54
	v_max3_u32 v24, v24, v26, v27
	v_sub_u32_e32 v28, v166, v54
	v_sub_u32_e32 v29, v167, v54
	v_max3_u32 v24, v24, v28, v29
	v_sub_u32_e32 v30, v168, v54
	v_sub_u32_e32 v31, v169, v54
	v_max3_u32 v24, v24, v30, v31
	v_sub_u32_e32 v32, v171, v54
	v_sub_u32_e32 v33, v172, v54
	v_max3_u32 v24, v24, v32, v33
	v_sub_u32_e32 v26, v173, v54
	v_sub_u32_e32 v27, v180, v54
	v_max3_u32 v24, v24, v26, v27
	v_sub_u32_e32 v28, v181, v54
	v_sub_u32_e32 v29, v182, v54
	v_max3_u32 v24, v24, v28, v29
	v_sub_u32_e32 v30, v0, v54
	v_sub_u32_e32 v31, v1, v54
	v_max3_u32 v24, v24, v30, v31
	v_sub_u32_e32 v32, v2, v54
	v_sub_u32_e32 v33, v3, v54
	v_max3_u32 v24, v24, v32, v33
	v_mov_b32_e32 v25, v24
	s_nop 1
	v_permlane16_swap_b32 v24, v25
	s_nop 1
	v_max_u32_e32 v24, v24, v25
	v_mov_b32_e32 v25, v24
	s_nop 1
	v_permlane32_swap_b32 v24, v25
	s_nop 1
	v_max_u32_e32 v24, v24, v25
	v_add_u32_e32 v55, v24, v54
	v_mov_b32_e32 v16, v40
	v_mov_b32_e32 v147, v41
	v_mov_b32_e32 v148, v42
	v_mov_b32_e32 v149, v43
	v_mov_b32_e32 v150, v44
	v_mov_b32_e32 v151, v45
	v_mov_b32_e32 v152, v46
	v_mov_b32_e32 v153, v47
	v_mov_b32_e32 v154, v48
	v_mov_b32_e32 v155, v49
	v_mov_b32_e32 v156, v50
	v_mov_b32_e32 v157, v51
	v_mov_b32_e32 v158, v52
	v_mov_b32_e32 v159, v53
	v_mov_b32_e32 v160, v54
	v_mov_b32_e32 v161, v55
	v_lshl_add_u64 v[236:237], v[88:89], 0, s[90:91]
	s_cmp_lg_u32 s88, 0
	s_cbranch_scc1 .Lp10q_mov1
; DI void peer_topk_wave(const Params& p, int item, unsigned* lds  ) {
;     ...
;     for (int ks = 0; ks < 4; ++ks) qf[ks] = *(const bf16x8*)&p.pq[(size_t)(row0 + r) * 2048 + h * 256 + pp * 128 + ks * 32 + kg * 8];
	global_load_dwordx4 v[12:15], v[88:89], off offset:256
	global_load_dwordx4 v[8:11], v[88:89], off offset:320
	global_load_dwordx4 v[4:7], v[88:89], off offset:384
	global_load_dwordx4 v[0:3], v[88:89], off offset:448
	s_branch .Lp10q_done1

; #define MFMA(a, b, c) __builtin_amdgcn_mfma_f32_16x16x32_bf16((a), (b), (c), 0, 0, 0)
; DI unsigned ordf(float f) { unsigned u = __float_as_uint(f); return (u & 0x80000000u) ? ~u : (u | 0x80000000u); }
; DI void peer_topk_wave(const Params& p, int item, unsigned* lds  ) {
;     ...
;     for (int ks = 0; ks < 4; ++ks) qf[ks] = *(const bf16x8*)&p.pq[(size_t)(row0 + r) * 2048 + h * 256 + pp * 128 + ks * 32 + kg * 8];
;     unsigned kk[32];
;     const u16* sk = p.subkb + (size_t)(h * 2 + pp) * 16384;
; #pragma unroll
;     for (int mt = 0; mt < 8; ++mt) {
;       f32x4 a = (f32x4){0.f, 0.f, 0.f, 0.f};
; #pragma unroll
;       for (int ks = 0; ks < 4; ++ks) {
;         bf16x8 kf = *(const bf16x8*)&sk[(mt * 16 + r) * 128 + ks * 32 + kg * 8];
;         a = MFMA(kf, qf[ks], a);
;       }
; #pragma unroll
;       for (int j = 0; j < 4; ++j) kk[mt * 4 + j] = (ordf(a[j]) & ~127u) | (unsigned)(mt * 16 + kg * 4 + j);
;     }
.Lp10q_done1:
	ds_bpermute_b32 v162, v112, v161
	v_readfirstlane_b32 s0, v86
	v_readfirstlane_b32 s1, v87
	s_nop 3
	s_add_u32 s0, s0, 0x8000
	s_addc_u32 s1, s1, 0
	s_add_u32 s2, s0, 0x0
	s_addc_u32 s3, s1, 0
	ds_read_b128 v[24:27], v241 offset:34816
	ds_read_b128 v[28:31], v241 offset:34880
	ds_read_b128 v[32:35], v241 offset:34944
	ds_read_b128 v[36:39], v241 offset:35008
	s_add_u32 s2, s0, 0x1000
	s_addc_u32 s3, s1, 0
	ds_read_b128 v[40:43], v241 offset:39168
	ds_read_b128 v[44:47], v241 offset:39232
	ds_read_b128 v[48:51], v241 offset:39296
	ds_read_b128 v[52:55], v241 offset:39360
	s_add_u32 s2, s0, 0x2000
	s_addc_u32 s3, s1, 0
	ds_read_b128 v[56:59], v241 offset:43520
	ds_read_b128 v[60:63], v241 offset:43584
	ds_read_b128 v[64:67], v241 offset:43648
	ds_read_b128 v[68:71], v241 offset:43712
	s_add_u32 s2, s0, 0x3000
	s_addc_u32 s3, s1, 0
	ds_read_b128 v[72:75], v241 offset:47872
	ds_read_b128 v[76:79], v241 offset:47936
	ds_read_b128 v[80:83], v241 offset:48000
	s_waitcnt vmcnt(0) lgkmcnt(11)
	v_mfma_f32_16x16x32_bf16 v[190:193], v[24:27], v[12:15], 0
	v_mfma_f32_16x16x32_bf16 v[190:193], v[28:31], v[8:11], v[190:193]
	v_mfma_f32_16x16x32_bf16 v[190:193], v[32:35], v[4:7], v[190:193]
	v_mfma_f32_16x16x32_bf16 v[190:193], v[36:39], v[0:3], v[190:193]
	ds_read_b128 v[24:27], v241 offset:48064
	s_add_u32 s2, s0, 0x4000
	s_addc_u32 s3, s1, 0
	ds_read_b128 v[28:31], v241 offset:52224
	ds_read_b128 v[32:35], v241 offset:52288
	ds_read_b128 v[36:39], v241 offset:52352
	s_waitcnt lgkmcnt(11)
	v_mfma_f32_16x16x32_bf16 v[198:201], v[40:43], v[12:15], 0
	v_mfma_f32_16x16x32_bf16 v[198:201], v[44:47], v[8:11], v[198:201]
	v_mfma_f32_16x16x32_bf16 v[198:201], v[48:51], v[4:7], v[198:201]
	v_mfma_f32_16x16x32_bf16 v[198:201], v[52:55], v[0:3], v[198:201]
	ds_read_b128 v[40:43], v241 offset:52416
	s_add_u32 s2, s0, 0x5000
	s_addc_u32 s3, s1, 0
	global_load_dwordx4 v[44:47], v20, s[2:3]
	global_load_dwordx4 v[48:51], v20, s[2:3] offset:64
	global_load_dwordx4 v[52:55], v20, s[2:3] offset:128
	s_nop 7
	s_nop 3
	v_ashrrev_i32_e32 v197, 31, v190
	v_or_b32_e32 v197, 0x80000000, v197
	v_xor_b32_e32 v197, v190, v197
	v_and_or_b32 v88, v197, s80, v170
	v_ashrrev_i32_e32 v202, 31, v191
	v_or_b32_e32 v202, 0x80000000, v202
	v_xor_b32_e32 v202, v191, v202
	v_and_or_b32 v89, v202, s80, v113
	v_ashrrev_i32_e32 v197, 31, v192
	v_or_b32_e32 v197, 0x80000000, v197
	v_xor_b32_e32 v197, v192, v197
	v_and_or_b32 v164, v197, s80, v114
	v_ashrrev_i32_e32 v202, 31, v193
	v_or_b32_e32 v202, 0x80000000, v202
	v_xor_b32_e32 v202, v193, v202
	v_and_or_b32 v165, v202, s80, v115
	s_waitcnt lgkmcnt(8)
	v_mfma_f32_16x16x32_bf16 v[190:193], v[56:59], v[12:15], 0
	v_mfma_f32_16x16x32_bf16 v[190:193], v[60:63], v[8:11], v[190:193]
	v_mfma_f32_16x16x32_bf16 v[190:193], v[64:67], v[4:7], v[190:193]
	v_mfma_f32_16x16x32_bf16 v[190:193], v[68:71], v[0:3], v[190:193]
	global_load_dwordx4 v[56:59], v20, s[2:3] offset:192
	s_add_u32 s2, s0, 0x6000
	s_addc_u32 s3, s1, 0
	global_load_dwordx4 v[60:63], v20, s[2:3]
	global_load_dwordx4 v[64:67], v20, s[2:3] offset:64
	global_load_dwordx4 v[68:71], v20, s[2:3] offset:128
	s_nop 7
	s_nop 3
	v_ashrrev_i32_e32 v197, 31, v198
	v_or_b32_e32 v197, 0x80000000, v197
	v_xor_b32_e32 v197, v198, v197
	v_and_or_b32 v166, v197, s80, v90
	v_ashrrev_i32_e32 v202, 31, v199
	v_or_b32_e32 v202, 0x80000000, v202
	v_xor_b32_e32 v202, v199, v202
	v_and_or_b32 v167, v202, s80, v116
	v_ashrrev_i32_e32 v197, 31, v200
	v_or_b32_e32 v197, 0x80000000, v197
	v_xor_b32_e32 v197, v200, v197
	v_and_or_b32 v168, v197, s80, v117
	v_ashrrev_i32_e32 v202, 31, v201
	v_or_b32_e32 v202, 0x80000000, v202
	v_xor_b32_e32 v202, v201, v202
	v_and_or_b32 v169, v202, s80, v118
	s_waitcnt lgkmcnt(4)
	v_mfma_f32_16x16x32_bf16 v[198:201], v[72:75], v[12:15], 0
	v_mfma_f32_16x16x32_bf16 v[198:201], v[76:79], v[8:11], v[198:201]
	v_mfma_f32_16x16x32_bf16 v[198:201], v[80:83], v[4:7], v[198:201]
	v_mfma_f32_16x16x32_bf16 v[198:201], v[24:27], v[0:3], v[198:201]
	global_load_dwordx4 v[72:75], v20, s[2:3] offset:192
	s_add_u32 s2, s0, 0x7000
	s_addc_u32 s3, s1, 0
	global_load_dwordx4 v[76:79], v20, s[2:3]
	global_load_dwordx4 v[80:83], v20, s[2:3] offset:64
	global_load_dwordx4 v[24:27], v20, s[2:3] offset:128
	s_nop 7
	s_nop 3
	v_ashrrev_i32_e32 v197, 31, v190
	v_or_b32_e32 v197, 0x80000000, v197
	v_xor_b32_e32 v197, v190, v197
	v_and_or_b32 v171, v197, s80, v91
	v_ashrrev_i32_e32 v202, 31, v191
	v_or_b32_e32 v202, 0x80000000, v202
	v_xor_b32_e32 v202, v191, v202
	v_and_or_b32 v172, v202, s80, v119
	v_ashrrev_i32_e32 v197, 31, v192
	v_or_b32_e32 v197, 0x80000000, v197
	v_xor_b32_e32 v197, v192, v197
	v_and_or_b32 v173, v197, s80, v120
	v_ashrrev_i32_e32 v202, 31, v193
	v_or_b32_e32 v202, 0x80000000, v202
	v_xor_b32_e32 v202, v193, v202
	v_and_or_b32 v176, v202, s80, v121
	s_waitcnt lgkmcnt(0)
	v_mfma_f32_16x16x32_bf16 v[190:193], v[28:31], v[12:15], 0
	v_mfma_f32_16x16x32_bf16 v[190:193], v[32:35], v[8:11], v[190:193]
	v_mfma_f32_16x16x32_bf16 v[190:193], v[36:39], v[4:7], v[190:193]
	v_mfma_f32_16x16x32_bf16 v[190:193], v[40:43], v[0:3], v[190:193]
	global_load_dwordx4 v[28:31], v20, s[2:3] offset:192
	s_nop 7
	s_nop 3
	v_ashrrev_i32_e32 v197, 31, v198
	v_or_b32_e32 v197, 0x80000000, v197
	v_xor_b32_e32 v197, v198, v197
	v_and_or_b32 v177, v197, s80, v92
	v_ashrrev_i32_e32 v202, 31, v199
	v_or_b32_e32 v202, 0x80000000, v202
	v_xor_b32_e32 v202, v199, v202
	v_and_or_b32 v178, v202, s80, v122
	v_ashrrev_i32_e32 v197, 31, v200
	v_or_b32_e32 v197, 0x80000000, v197
	v_xor_b32_e32 v197, v200, v197
	v_and_or_b32 v179, v197, s80, v123
	v_ashrrev_i32_e32 v202, 31, v201
	v_or_b32_e32 v202, 0x80000000, v202
	v_xor_b32_e32 v202, v201, v202
	v_and_or_b32 v180, v202, s80, v124
	s_waitcnt vmcnt(8)
; #define MFMA(a, b, c) __builtin_amdgcn_mfma_f32_16x16x32_bf16((a), (b), (c), 0, 0, 0)
; DI unsigned ordf(float f) { unsigned u = __float_as_uint(f); return (u & 0x80000000u) ? ~u : (u | 0x80000000u); }
; DI void peer_topk_wave(const Params& p, int item, unsigned* lds  ) {
;     ...
;     for (int ks = 0; ks < 4; ++ks) qf[ks] = *(const bf16x8*)&p.pq[(size_t)(row0 + r) * 2048 + h * 256 + pp * 128 + ks * 32 + kg * 8];
;     unsigned kk[32];
;     const u16* sk = p.subkb + (size_t)(h * 2 + pp) * 16384;
; #pragma unroll
;     for (int mt = 0; mt < 8; ++mt) {
;       f32x4 a = (f32x4){0.f, 0.f, 0.f, 0.f};
; #pragma unroll
;       for (int ks = 0; ks < 4; ++ks) {
;         bf16x8 kf = *(const bf16x8*)&sk[(mt * 16 + r) * 128 + ks * 32 + kg * 8];
;         a = MFMA(kf, qf[ks], a);
;       }
; #pragma unroll
;       for (int j = 0; j < 4; ++j) kk[mt * 4 + j] = (ordf(a[j]) & ~127u) | (unsigned)(mt * 16 + kg * 4 + j);
;     }
; #pragma unroll
;     for (int rr = 0; rr < 16; ++rr) {
;       unsigned m = 0;
; #pragma unroll
;       for (int i = 0; i < 32; ++i) m = umax(m, kk[i]);
;       m = umax(m, (unsigned)__shfl_xor((int)m, 16));
;       m = umax(m, (unsigned)__shfl_xor((int)m, 32));
;       win[pp][rr] = m;
; #pragma unroll
;       for (int i = 0; i < 32; ++i) kk[i] = (kk[i] == m) ? 0u : kk[i];
	v_mfma_f32_16x16x32_bf16 v[198:201], v[44:47], v[12:15], 0
	v_mfma_f32_16x16x32_bf16 v[198:201], v[48:51], v[8:11], v[198:201]
	v_mfma_f32_16x16x32_bf16 v[198:201], v[52:55], v[4:7], v[198:201]
	v_mfma_f32_16x16x32_bf16 v[198:201], v[56:59], v[0:3], v[198:201]
	s_nop 7
	s_nop 3
	v_ashrrev_i32_e32 v197, 31, v190
	v_or_b32_e32 v197, 0x80000000, v197
	v_xor_b32_e32 v197, v190, v197
	v_and_or_b32 v181, v197, s80, v93
	v_ashrrev_i32_e32 v202, 31, v191
	v_or_b32_e32 v202, 0x80000000, v202
	v_xor_b32_e32 v202, v191, v202
	v_and_or_b32 v182, v202, s80, v125
	v_ashrrev_i32_e32 v197, 31, v192
	v_or_b32_e32 v197, 0x80000000, v197
	v_xor_b32_e32 v197, v192, v197
	v_and_or_b32 v183, v197, s80, v126
	v_ashrrev_i32_e32 v202, 31, v193
	v_or_b32_e32 v202, 0x80000000, v202
	v_xor_b32_e32 v202, v193, v202
	v_and_or_b32 v184, v202, s80, v127
	s_waitcnt vmcnt(4)
	v_mfma_f32_16x16x32_bf16 v[190:193], v[60:63], v[12:15], 0
	v_mfma_f32_16x16x32_bf16 v[190:193], v[64:67], v[8:11], v[190:193]
	v_mfma_f32_16x16x32_bf16 v[190:193], v[68:71], v[4:7], v[190:193]
	v_mfma_f32_16x16x32_bf16 v[190:193], v[72:75], v[0:3], v[190:193]
	s_nop 7
	s_nop 3
	v_ashrrev_i32_e32 v197, 31, v198
	v_or_b32_e32 v197, 0x80000000, v197
	v_xor_b32_e32 v197, v198, v197
	v_and_or_b32 v185, v197, s80, v94
	v_ashrrev_i32_e32 v202, 31, v199
	v_or_b32_e32 v202, 0x80000000, v202
	v_xor_b32_e32 v202, v199, v202
	v_and_or_b32 v186, v202, s80, v129
	v_ashrrev_i32_e32 v197, 31, v200
	v_or_b32_e32 v197, 0x80000000, v197
	v_xor_b32_e32 v197, v200, v197
	v_and_or_b32 v187, v197, s80, v130
	v_ashrrev_i32_e32 v202, 31, v201
	v_or_b32_e32 v202, 0x80000000, v202
	v_xor_b32_e32 v202, v201, v202
	v_and_or_b32 v188, v202, s80, v131
	s_waitcnt vmcnt(0)
	v_mfma_f32_16x16x32_bf16 v[198:201], v[76:79], v[12:15], 0
	v_mfma_f32_16x16x32_bf16 v[198:201], v[80:83], v[8:11], v[198:201]
	v_mfma_f32_16x16x32_bf16 v[198:201], v[24:27], v[4:7], v[198:201]
	v_mfma_f32_16x16x32_bf16 v[198:201], v[28:31], v[0:3], v[198:201]
	s_nop 7
	s_nop 3
	v_ashrrev_i32_e32 v197, 31, v190
	v_or_b32_e32 v197, 0x80000000, v197
	v_xor_b32_e32 v197, v190, v197
	v_and_or_b32 v189, v197, s80, v95
	v_ashrrev_i32_e32 v202, 31, v191
	v_or_b32_e32 v202, 0x80000000, v202
	v_xor_b32_e32 v202, v191, v202
	v_and_or_b32 v194, v202, s80, v135
	v_ashrrev_i32_e32 v197, 31, v192
	v_or_b32_e32 v197, 0x80000000, v197
	v_xor_b32_e32 v197, v192, v197
	v_and_or_b32 v195, v197, s80, v136
	v_ashrrev_i32_e32 v202, 31, v193
	v_or_b32_e32 v202, 0x80000000, v202
	v_xor_b32_e32 v202, v193, v202
	v_and_or_b32 v196, v202, s80, v137
	s_nop 7
	s_nop 3
	v_ashrrev_i32_e32 v197, 31, v198
	v_or_b32_e32 v197, 0x80000000, v197
	v_xor_b32_e32 v197, v198, v197
	v_and_or_b32 v4, v197, s80, v96
	v_ashrrev_i32_e32 v202, 31, v199
	v_or_b32_e32 v202, 0x80000000, v202
	v_xor_b32_e32 v202, v199, v202
	v_and_or_b32 v1, v202, s80, v138
	v_ashrrev_i32_e32 v197, 31, v200
	v_or_b32_e32 v197, 0x80000000, v197
	v_xor_b32_e32 v197, v200, v197
	v_and_or_b32 v2, v197, s80, v139
	v_ashrrev_i32_e32 v202, 31, v201
	v_or_b32_e32 v202, 0x80000000, v202
	v_xor_b32_e32 v202, v201, v202
	v_and_or_b32 v3, v202, s80, v140
	global_load_dwordx4 v[204:207], v[236:237], off
	global_load_dwordx4 v[208:211], v[236:237], off offset:64
	global_load_dwordx4 v[212:215], v[236:237], off offset:128
	global_load_dwordx4 v[216:219], v[236:237], off offset:192
	global_load_dwordx4 v[220:223], v[236:237], off offset:256
	global_load_dwordx4 v[224:227], v[236:237], off offset:320
	global_load_dwordx4 v[228:231], v[236:237], off offset:384
	global_load_dwordx4 v[232:235], v[236:237], off offset:448
	s_mov_b32 s88, 1
	v_max_u32_e32 v24, v88, v89
	v_max3_u32 v24, v24, v164, v165
	v_max3_u32 v24, v24, v166, v167
	v_max3_u32 v24, v24, v168, v169
	v_max3_u32 v24, v24, v171, v172
	v_max3_u32 v24, v24, v173, v176
	v_max3_u32 v24, v24, v177, v178
	v_max3_u32 v24, v24, v179, v180
	v_max3_u32 v24, v24, v181, v182
	v_max3_u32 v24, v24, v183, v184
	v_max3_u32 v24, v24, v185, v186
	v_max3_u32 v24, v24, v187, v188
	v_max3_u32 v24, v24, v189, v194
	v_max3_u32 v24, v24, v195, v196
	v_max3_u32 v24, v24, v4, v1
	v_max3_u32 v24, v24, v2, v3
	v_mov_b32_e32 v25, v24
	s_nop 1
	v_permlane16_swap_b32 v24, v25
	s_nop 1
	v_max_u32_e32 v24, v24, v25
	v_mov_b32_e32 v25, v24
	s_nop 1
	v_permlane32_swap_b32 v24, v25
	s_nop 1
	v_max_u32_e32 v40, v24, v25
	v_sub_u32_e32 v26, v88, v40
	v_sub_u32_e32 v27, v89, v40
	v_max_u32_e32 v24, v26, v27
	v_sub_u32_e32 v28, v164, v40
	v_sub_u32_e32 v29, v165, v40
	v_max3_u32 v24, v24, v28, v29
	v_sub_u32_e32 v30, v166, v40
	v_sub_u32_e32 v31, v167, v40
	v_max3_u32 v24, v24, v30, v31
	v_sub_u32_e32 v32, v168, v40
	v_sub_u32_e32 v33, v169, v40
	v_max3_u32 v24, v24, v32, v33
	v_sub_u32_e32 v26, v171, v40
	v_sub_u32_e32 v27, v172, v40
	v_max3_u32 v24, v24, v26, v27
	v_sub_u32_e32 v28, v173, v40
	v_sub_u32_e32 v29, v176, v40
	v_max3_u32 v24, v24, v28, v29
	v_sub_u32_e32 v30, v177, v40
	v_sub_u32_e32 v31, v178, v40
	v_max3_u32 v24, v24, v30, v31
	v_sub_u32_e32 v32, v179, v40
	v_sub_u32_e32 v33, v180, v40
	v_max3_u32 v24, v24, v32, v33
	v_sub_u32_e32 v26, v181, v40
	v_sub_u32_e32 v27, v182, v40
	v_max3_u32 v24, v24, v26, v27
	v_sub_u32_e32 v28, v183, v40
	v_sub_u32_e32 v29, v184, v40
	v_max3_u32 v24, v24, v28, v29
	v_sub_u32_e32 v30, v185, v40
	v_sub_u32_e32 v31, v186, v40
	v_max3_u32 v24, v24, v30, v31
	v_sub_u32_e32 v32, v187, v40
	v_sub_u32_e32 v33, v188, v40
	v_max3_u32 v24, v24, v32, v33
	v_sub_u32_e32 v26, v189, v40
	v_sub_u32_e32 v27, v194, v40
	v_max3_u32 v24, v24, v26, v27
	v_sub_u32_e32 v28, v195, v40
	v_sub_u32_e32 v29, v196, v40
	v_max3_u32 v24, v24, v28, v29
	v_sub_u32_e32 v30, v4, v40
	v_sub_u32_e32 v31, v1, v40
; DI void peer_topk_wave(const Params& p, int item, unsigned* lds  ) {
;     ...
;     for (int rr = 0; rr < 16; ++rr) {
;       unsigned m = 0;
; #pragma unroll
;       for (int i = 0; i < 32; ++i) m = umax(m, kk[i]);
;       m = umax(m, (unsigned)__shfl_xor((int)m, 16));
;       m = umax(m, (unsigned)__shfl_xor((int)m, 32));
;       win[pp][rr] = m;
; #pragma unroll
;       for (int i = 0; i < 32; ++i) kk[i] = (kk[i] == m) ? 0u : kk[i];
	v_max3_u32 v24, v24, v30, v31
	v_sub_u32_e32 v32, v2, v40
	v_sub_u32_e32 v33, v3, v40
	v_max3_u32 v24, v24, v32, v33
	v_mov_b32_e32 v25, v24
	s_nop 1
	v_permlane16_swap_b32 v24, v25
	s_nop 1
	v_max_u32_e32 v24, v24, v25
	v_mov_b32_e32 v25, v24
	s_nop 1
	v_permlane32_swap_b32 v24, v25
	s_nop 1
	v_max_u32_e32 v24, v24, v25
	v_add_u32_e32 v41, v24, v40
	v_sub_u32_e32 v26, v88, v41
	v_sub_u32_e32 v27, v89, v41
	v_max_u32_e32 v24, v26, v27
	v_sub_u32_e32 v28, v164, v41
	v_sub_u32_e32 v29, v165, v41
	v_max3_u32 v24, v24, v28, v29
	v_sub_u32_e32 v30, v166, v41
	v_sub_u32_e32 v31, v167, v41
	v_max3_u32 v24, v24, v30, v31
	v_sub_u32_e32 v32, v168, v41
	v_sub_u32_e32 v33, v169, v41
	v_max3_u32 v24, v24, v32, v33
	v_sub_u32_e32 v26, v171, v41
	v_sub_u32_e32 v27, v172, v41
	v_max3_u32 v24, v24, v26, v27
	v_sub_u32_e32 v28, v173, v41
	v_sub_u32_e32 v29, v176, v41
	v_max3_u32 v24, v24, v28, v29
	v_sub_u32_e32 v30, v177, v41
	v_sub_u32_e32 v31, v178, v41
	v_max3_u32 v24, v24, v30, v31
	v_sub_u32_e32 v32, v179, v41
	v_sub_u32_e32 v33, v180, v41
	v_max3_u32 v24, v24, v32, v33
	v_sub_u32_e32 v26, v181, v41
	v_sub_u32_e32 v27, v182, v41
	v_max3_u32 v24, v24, v26, v27
	v_sub_u32_e32 v28, v183, v41
	v_sub_u32_e32 v29, v184, v41
	v_max3_u32 v24, v24, v28, v29
	v_sub_u32_e32 v30, v185, v41
	v_sub_u32_e32 v31, v186, v41
	v_max3_u32 v24, v24, v30, v31
	v_sub_u32_e32 v32, v187, v41
	v_sub_u32_e32 v33, v188, v41
	v_max3_u32 v24, v24, v32, v33
	v_sub_u32_e32 v26, v189, v41
	v_sub_u32_e32 v27, v194, v41
	v_max3_u32 v24, v24, v26, v27
	v_sub_u32_e32 v28, v195, v41
	v_sub_u32_e32 v29, v196, v41
	v_max3_u32 v24, v24, v28, v29
	v_sub_u32_e32 v30, v4, v41
	v_sub_u32_e32 v31, v1, v41
	v_max3_u32 v24, v24, v30, v31
	v_sub_u32_e32 v32, v2, v41
	v_sub_u32_e32 v33, v3, v41
	v_max3_u32 v24, v24, v32, v33
	v_mov_b32_e32 v25, v24
	s_nop 1
	v_permlane16_swap_b32 v24, v25
	s_nop 1
	v_max_u32_e32 v24, v24, v25
	v_mov_b32_e32 v25, v24
	s_nop 1
	v_permlane32_swap_b32 v24, v25
	s_nop 1
	v_max_u32_e32 v24, v24, v25
	v_add_u32_e32 v42, v24, v41
	v_sub_u32_e32 v26, v88, v42
	v_sub_u32_e32 v27, v89, v42
	v_max_u32_e32 v24, v26, v27
	v_sub_u32_e32 v28, v164, v42
	v_sub_u32_e32 v29, v165, v42
	v_max3_u32 v24, v24, v28, v29
	v_sub_u32_e32 v30, v166, v42
	v_sub_u32_e32 v31, v167, v42
	v_max3_u32 v24, v24, v30, v31
	v_sub_u32_e32 v32, v168, v42
	v_sub_u32_e32 v33, v169, v42
	v_max3_u32 v24, v24, v32, v33
	v_sub_u32_e32 v26, v171, v42
	v_sub_u32_e32 v27, v172, v42
	v_max3_u32 v24, v24, v26, v27
	v_sub_u32_e32 v28, v173, v42
	v_sub_u32_e32 v29, v176, v42
	v_max3_u32 v24, v24, v28, v29
	v_sub_u32_e32 v30, v177, v42
	v_sub_u32_e32 v31, v178, v42
	v_max3_u32 v24, v24, v30, v31
	v_sub_u32_e32 v32, v179, v42
	v_sub_u32_e32 v33, v180, v42
	v_max3_u32 v24, v24, v32, v33
	v_sub_u32_e32 v26, v181, v42
	v_sub_u32_e32 v27, v182, v42
	v_max3_u32 v24, v24, v26, v27
	v_sub_u32_e32 v28, v183, v42
	v_sub_u32_e32 v29, v184, v42
	v_max3_u32 v24, v24, v28, v29
	v_sub_u32_e32 v30, v185, v42
	v_sub_u32_e32 v31, v186, v42
	v_max3_u32 v24, v24, v30, v31
	v_sub_u32_e32 v32, v187, v42
	v_sub_u32_e32 v33, v188, v42
	v_max3_u32 v24, v24, v32, v33
	v_sub_u32_e32 v26, v189, v42
	v_sub_u32_e32 v27, v194, v42
	v_max3_u32 v24, v24, v26, v27
	v_sub_u32_e32 v28, v195, v42
	v_sub_u32_e32 v29, v196, v42
	v_max3_u32 v24, v24, v28, v29
	v_sub_u32_e32 v30, v4, v42
	v_sub_u32_e32 v31, v1, v42
	v_max3_u32 v24, v24, v30, v31
	v_sub_u32_e32 v32, v2, v42
	v_sub_u32_e32 v33, v3, v42
	v_max3_u32 v24, v24, v32, v33
	v_mov_b32_e32 v25, v24
	s_nop 1
	v_permlane16_swap_b32 v24, v25
	s_nop 1
	v_max_u32_e32 v24, v24, v25
	v_mov_b32_e32 v25, v24
	s_nop 1
	v_permlane32_swap_b32 v24, v25
	s_nop 1
	v_max_u32_e32 v24, v24, v25
	v_add_u32_e32 v43, v24, v42
	v_sub_u32_e32 v26, v88, v43
	v_sub_u32_e32 v27, v89, v43
	v_max_u32_e32 v24, v26, v27
	v_sub_u32_e32 v28, v164, v43
	v_sub_u32_e32 v29, v165, v43
	v_max3_u32 v24, v24, v28, v29
	v_sub_u32_e32 v30, v166, v43
	v_sub_u32_e32 v31, v167, v43
	v_max3_u32 v24, v24, v30, v31
	v_sub_u32_e32 v32, v168, v43
	v_sub_u32_e32 v33, v169, v43
	v_max3_u32 v24, v24, v32, v33
	v_sub_u32_e32 v26, v171, v43
	v_sub_u32_e32 v27, v172, v43
	v_max3_u32 v24, v24, v26, v27
	v_sub_u32_e32 v28, v173, v43
	v_sub_u32_e32 v29, v176, v43
	v_max3_u32 v24, v24, v28, v29
	v_sub_u32_e32 v30, v177, v43
	v_sub_u32_e32 v31, v178, v43
	v_max3_u32 v24, v24, v30, v31
	v_sub_u32_e32 v32, v179, v43
	v_sub_u32_e32 v33, v180, v43
	v_max3_u32 v24, v24, v32, v33
	v_sub_u32_e32 v26, v181, v43
	v_sub_u32_e32 v27, v182, v43
	v_max3_u32 v24, v24, v26, v27
	v_sub_u32_e32 v28, v183, v43
	v_sub_u32_e32 v29, v184, v43
	v_max3_u32 v24, v24, v28, v29
	v_sub_u32_e32 v30, v185, v43
	v_sub_u32_e32 v31, v186, v43
	v_max3_u32 v24, v24, v30, v31
	v_sub_u32_e32 v32, v187, v43
	v_sub_u32_e32 v33, v188, v43
	v_max3_u32 v24, v24, v32, v33
	v_sub_u32_e32 v26, v189, v43
	v_sub_u32_e32 v27, v194, v43
	v_max3_u32 v24, v24, v26, v27
	v_sub_u32_e32 v28, v195, v43
	v_sub_u32_e32 v29, v196, v43
	v_max3_u32 v24, v24, v28, v29
	v_sub_u32_e32 v30, v4, v43
	v_sub_u32_e32 v31, v1, v43
	v_max3_u32 v24, v24, v30, v31
	v_sub_u32_e32 v32, v2, v43
	v_sub_u32_e32 v33, v3, v43
	v_max3_u32 v24, v24, v32, v33
	v_mov_b32_e32 v25, v24
	s_nop 1
	v_permlane16_swap_b32 v24, v25
	s_nop 1
	v_max_u32_e32 v24, v24, v25
	v_mov_b32_e32 v25, v24
	s_nop 1
	v_permlane32_swap_b32 v24, v25
	s_nop 1
	v_max_u32_e32 v24, v24, v25
	v_add_u32_e32 v44, v24, v43
	v_sub_u32_e32 v26, v88, v44
	v_sub_u32_e32 v27, v89, v44
	v_max_u32_e32 v24, v26, v27
	v_sub_u32_e32 v28, v164, v44
	v_sub_u32_e32 v29, v165, v44
	v_max3_u32 v24, v24, v28, v29
	v_sub_u32_e32 v30, v166, v44
	v_sub_u32_e32 v31, v167, v44
; DI void peer_topk_wave(const Params& p, int item, unsigned* lds  ) {
;     ...
;     for (int rr = 0; rr < 16; ++rr) {
;       unsigned m = 0;
; #pragma unroll
;       for (int i = 0; i < 32; ++i) m = umax(m, kk[i]);
;       m = umax(m, (unsigned)__shfl_xor((int)m, 16));
;       m = umax(m, (unsigned)__shfl_xor((int)m, 32));
;       win[pp][rr] = m;
; #pragma unroll
;       for (int i = 0; i < 32; ++i) kk[i] = (kk[i] == m) ? 0u : kk[i];
	v_max3_u32 v24, v24, v30, v31
	v_sub_u32_e32 v32, v168, v44
	v_sub_u32_e32 v33, v169, v44
	v_max3_u32 v24, v24, v32, v33
	v_sub_u32_e32 v26, v171, v44
	v_sub_u32_e32 v27, v172, v44
	v_max3_u32 v24, v24, v26, v27
	v_sub_u32_e32 v28, v173, v44
	v_sub_u32_e32 v29, v176, v44
	v_max3_u32 v24, v24, v28, v29
	v_sub_u32_e32 v30, v177, v44
	v_sub_u32_e32 v31, v178, v44
	v_max3_u32 v24, v24, v30, v31
	v_sub_u32_e32 v32, v179, v44
	v_sub_u32_e32 v33, v180, v44
	v_max3_u32 v24, v24, v32, v33
	v_sub_u32_e32 v26, v181, v44
	v_sub_u32_e32 v27, v182, v44
	v_max3_u32 v24, v24, v26, v27
	v_sub_u32_e32 v28, v183, v44
	v_sub_u32_e32 v29, v184, v44
	v_max3_u32 v24, v24, v28, v29
	v_sub_u32_e32 v30, v185, v44
	v_sub_u32_e32 v31, v186, v44
	v_max3_u32 v24, v24, v30, v31
	v_sub_u32_e32 v32, v187, v44
	v_sub_u32_e32 v33, v188, v44
	v_max3_u32 v24, v24, v32, v33
	v_sub_u32_e32 v26, v189, v44
	v_sub_u32_e32 v27, v194, v44
	v_max3_u32 v24, v24, v26, v27
	v_sub_u32_e32 v28, v195, v44
	v_sub_u32_e32 v29, v196, v44
	v_max3_u32 v24, v24, v28, v29
	v_sub_u32_e32 v30, v4, v44
	v_sub_u32_e32 v31, v1, v44
	v_max3_u32 v24, v24, v30, v31
	v_sub_u32_e32 v32, v2, v44
	v_sub_u32_e32 v33, v3, v44
	v_max3_u32 v24, v24, v32, v33
	v_mov_b32_e32 v25, v24
	s_nop 1
	v_permlane16_swap_b32 v24, v25
	s_nop 1
	v_max_u32_e32 v24, v24, v25
	v_mov_b32_e32 v25, v24
	s_nop 1
	v_permlane32_swap_b32 v24, v25
	s_nop 1
	v_max_u32_e32 v24, v24, v25
	v_add_u32_e32 v45, v24, v44
	v_sub_u32_e32 v26, v88, v45
	v_sub_u32_e32 v27, v89, v45
	v_max_u32_e32 v24, v26, v27
	v_sub_u32_e32 v28, v164, v45
	v_sub_u32_e32 v29, v165, v45
	v_max3_u32 v24, v24, v28, v29
	v_sub_u32_e32 v30, v166, v45
	v_sub_u32_e32 v31, v167, v45
	v_max3_u32 v24, v24, v30, v31
	v_sub_u32_e32 v32, v168, v45
	v_sub_u32_e32 v33, v169, v45
	v_max3_u32 v24, v24, v32, v33
	v_sub_u32_e32 v26, v171, v45
	v_sub_u32_e32 v27, v172, v45
	v_max3_u32 v24, v24, v26, v27
	v_sub_u32_e32 v28, v173, v45
	v_sub_u32_e32 v29, v176, v45
	v_max3_u32 v24, v24, v28, v29
	v_sub_u32_e32 v30, v177, v45
	v_sub_u32_e32 v31, v178, v45
	v_max3_u32 v24, v24, v30, v31
	v_sub_u32_e32 v32, v179, v45
	v_sub_u32_e32 v33, v180, v45
	v_max3_u32 v24, v24, v32, v33
	v_sub_u32_e32 v26, v181, v45
	v_sub_u32_e32 v27, v182, v45
	v_max3_u32 v24, v24, v26, v27
	v_sub_u32_e32 v28, v183, v45
	v_sub_u32_e32 v29, v184, v45
	v_max3_u32 v24, v24, v28, v29
	v_sub_u32_e32 v30, v185, v45
	v_sub_u32_e32 v31, v186, v45
	v_max3_u32 v24, v24, v30, v31
	v_sub_u32_e32 v32, v187, v45
	v_sub_u32_e32 v33, v188, v45
	v_max3_u32 v24, v24, v32, v33
	v_sub_u32_e32 v26, v189, v45
	v_sub_u32_e32 v27, v194, v45
	v_max3_u32 v24, v24, v26, v27
	v_sub_u32_e32 v28, v195, v45
	v_sub_u32_e32 v29, v196, v45
	v_max3_u32 v24, v24, v28, v29
	v_sub_u32_e32 v30, v4, v45
	v_sub_u32_e32 v31, v1, v45
	v_max3_u32 v24, v24, v30, v31
	v_sub_u32_e32 v32, v2, v45
	v_sub_u32_e32 v33, v3, v45
	v_max3_u32 v24, v24, v32, v33
	v_mov_b32_e32 v25, v24
	s_nop 1
	v_permlane16_swap_b32 v24, v25
	s_nop 1
	v_max_u32_e32 v24, v24, v25
	v_mov_b32_e32 v25, v24
	s_nop 1
	v_permlane32_swap_b32 v24, v25
	s_nop 1
	v_max_u32_e32 v24, v24, v25
	v_add_u32_e32 v46, v24, v45
	v_sub_u32_e32 v26, v88, v46
	v_sub_u32_e32 v27, v89, v46
	v_max_u32_e32 v24, v26, v27
	v_sub_u32_e32 v28, v164, v46
	v_sub_u32_e32 v29, v165, v46
	v_max3_u32 v24, v24, v28, v29
	v_sub_u32_e32 v30, v166, v46
	v_sub_u32_e32 v31, v167, v46
	v_max3_u32 v24, v24, v30, v31
	v_sub_u32_e32 v32, v168, v46
	v_sub_u32_e32 v33, v169, v46
	v_max3_u32 v24, v24, v32, v33
	v_sub_u32_e32 v26, v171, v46
	v_sub_u32_e32 v27, v172, v46
	v_max3_u32 v24, v24, v26, v27
	v_sub_u32_e32 v28, v173, v46
	v_sub_u32_e32 v29, v176, v46
	v_max3_u32 v24, v24, v28, v29
	v_sub_u32_e32 v30, v177, v46
	v_sub_u32_e32 v31, v178, v46
	v_max3_u32 v24, v24, v30, v31
	v_sub_u32_e32 v32, v179, v46
	v_sub_u32_e32 v33, v180, v46
	v_max3_u32 v24, v24, v32, v33
	v_sub_u32_e32 v26, v181, v46
	v_sub_u32_e32 v27, v182, v46
	v_max3_u32 v24, v24, v26, v27
	v_sub_u32_e32 v28, v183, v46
	v_sub_u32_e32 v29, v184, v46
	v_max3_u32 v24, v24, v28, v29
	v_sub_u32_e32 v30, v185, v46
	v_sub_u32_e32 v31, v186, v46
	v_max3_u32 v24, v24, v30, v31
	v_sub_u32_e32 v32, v187, v46
	v_sub_u32_e32 v33, v188, v46
	v_max3_u32 v24, v24, v32, v33
	v_sub_u32_e32 v26, v189, v46
	v_sub_u32_e32 v27, v194, v46
	v_max3_u32 v24, v24, v26, v27
	v_sub_u32_e32 v28, v195, v46
	v_sub_u32_e32 v29, v196, v46
	v_max3_u32 v24, v24, v28, v29
	v_sub_u32_e32 v30, v4, v46
	v_sub_u32_e32 v31, v1, v46
	v_max3_u32 v24, v24, v30, v31
	v_sub_u32_e32 v32, v2, v46
	v_sub_u32_e32 v33, v3, v46
	v_max3_u32 v24, v24, v32, v33
	v_mov_b32_e32 v25, v24
	s_nop 1
	v_permlane16_swap_b32 v24, v25
	s_nop 1
	v_max_u32_e32 v24, v24, v25
	v_mov_b32_e32 v25, v24
	s_nop 1
	v_permlane32_swap_b32 v24, v25
	s_nop 1
	v_max_u32_e32 v24, v24, v25
	v_add_u32_e32 v47, v24, v46
	v_sub_u32_e32 v26, v88, v47
	v_sub_u32_e32 v27, v89, v47
	v_max_u32_e32 v24, v26, v27
	v_sub_u32_e32 v28, v164, v47
	v_sub_u32_e32 v29, v165, v47
	v_max3_u32 v24, v24, v28, v29
	v_sub_u32_e32 v30, v166, v47
	v_sub_u32_e32 v31, v167, v47
	v_max3_u32 v24, v24, v30, v31
	v_sub_u32_e32 v32, v168, v47
	v_sub_u32_e32 v33, v169, v47
	v_max3_u32 v24, v24, v32, v33
	v_sub_u32_e32 v26, v171, v47
	v_sub_u32_e32 v27, v172, v47
	v_max3_u32 v24, v24, v26, v27
	v_sub_u32_e32 v28, v173, v47
	v_sub_u32_e32 v29, v176, v47
	v_max3_u32 v24, v24, v28, v29
	v_sub_u32_e32 v30, v177, v47
	v_sub_u32_e32 v31, v178, v47
	v_max3_u32 v24, v24, v30, v31
	v_sub_u32_e32 v32, v179, v47
	v_sub_u32_e32 v33, v180, v47
	v_max3_u32 v24, v24, v32, v33
	v_sub_u32_e32 v26, v181, v47
	v_sub_u32_e32 v27, v182, v47
	v_max3_u32 v24, v24, v26, v27
	v_sub_u32_e32 v28, v183, v47
; DI void peer_topk_wave(const Params& p, int item, unsigned* lds  ) {
;     ...
;     for (int rr = 0; rr < 16; ++rr) {
;       unsigned m = 0;
; #pragma unroll
;       for (int i = 0; i < 32; ++i) m = umax(m, kk[i]);
;       m = umax(m, (unsigned)__shfl_xor((int)m, 16));
;       m = umax(m, (unsigned)__shfl_xor((int)m, 32));
;       win[pp][rr] = m;
; #pragma unroll
;       for (int i = 0; i < 32; ++i) kk[i] = (kk[i] == m) ? 0u : kk[i];
	v_sub_u32_e32 v29, v184, v47
	v_max3_u32 v24, v24, v28, v29
	v_sub_u32_e32 v30, v185, v47
	v_sub_u32_e32 v31, v186, v47
	v_max3_u32 v24, v24, v30, v31
	v_sub_u32_e32 v32, v187, v47
	v_sub_u32_e32 v33, v188, v47
	v_max3_u32 v24, v24, v32, v33
	v_sub_u32_e32 v26, v189, v47
	v_sub_u32_e32 v27, v194, v47
	v_max3_u32 v24, v24, v26, v27
	v_sub_u32_e32 v28, v195, v47
	v_sub_u32_e32 v29, v196, v47
	v_max3_u32 v24, v24, v28, v29
	v_sub_u32_e32 v30, v4, v47
	v_sub_u32_e32 v31, v1, v47
	v_max3_u32 v24, v24, v30, v31
	v_sub_u32_e32 v32, v2, v47
	v_sub_u32_e32 v33, v3, v47
	v_max3_u32 v24, v24, v32, v33
	v_mov_b32_e32 v25, v24
	s_nop 1
	v_permlane16_swap_b32 v24, v25
	s_nop 1
	v_max_u32_e32 v24, v24, v25
	v_mov_b32_e32 v25, v24
	s_nop 1
	v_permlane32_swap_b32 v24, v25
	s_nop 1
	v_max_u32_e32 v24, v24, v25
	v_add_u32_e32 v48, v24, v47
	v_sub_u32_e32 v26, v88, v48
	v_sub_u32_e32 v27, v89, v48
	v_max_u32_e32 v24, v26, v27
	v_sub_u32_e32 v28, v164, v48
	v_sub_u32_e32 v29, v165, v48
	v_max3_u32 v24, v24, v28, v29
	v_sub_u32_e32 v30, v166, v48
	v_sub_u32_e32 v31, v167, v48
	v_max3_u32 v24, v24, v30, v31
	v_sub_u32_e32 v32, v168, v48
	v_sub_u32_e32 v33, v169, v48
	v_max3_u32 v24, v24, v32, v33
	v_sub_u32_e32 v26, v171, v48
	v_sub_u32_e32 v27, v172, v48
	v_max3_u32 v24, v24, v26, v27
	v_sub_u32_e32 v28, v173, v48
	v_sub_u32_e32 v29, v176, v48
	v_max3_u32 v24, v24, v28, v29
	v_sub_u32_e32 v30, v177, v48
	v_sub_u32_e32 v31, v178, v48
	v_max3_u32 v24, v24, v30, v31
	v_sub_u32_e32 v32, v179, v48
	v_sub_u32_e32 v33, v180, v48
	v_max3_u32 v24, v24, v32, v33
	v_sub_u32_e32 v26, v181, v48
	v_sub_u32_e32 v27, v182, v48
	v_max3_u32 v24, v24, v26, v27
	v_sub_u32_e32 v28, v183, v48
	v_sub_u32_e32 v29, v184, v48
	v_max3_u32 v24, v24, v28, v29
	v_sub_u32_e32 v30, v185, v48
	v_sub_u32_e32 v31, v186, v48
	v_max3_u32 v24, v24, v30, v31
	v_sub_u32_e32 v32, v187, v48
	v_sub_u32_e32 v33, v188, v48
	v_max3_u32 v24, v24, v32, v33
	v_sub_u32_e32 v26, v189, v48
	v_sub_u32_e32 v27, v194, v48
	v_max3_u32 v24, v24, v26, v27
	v_sub_u32_e32 v28, v195, v48
	v_sub_u32_e32 v29, v196, v48
	v_max3_u32 v24, v24, v28, v29
	v_sub_u32_e32 v30, v4, v48
	v_sub_u32_e32 v31, v1, v48
	v_max3_u32 v24, v24, v30, v31
	v_sub_u32_e32 v32, v2, v48
	v_sub_u32_e32 v33, v3, v48
	v_max3_u32 v24, v24, v32, v33
	v_mov_b32_e32 v25, v24
	s_nop 1
	v_permlane16_swap_b32 v24, v25
	s_nop 1
	v_max_u32_e32 v24, v24, v25
	v_mov_b32_e32 v25, v24
	s_nop 1
	v_permlane32_swap_b32 v24, v25
	s_nop 1
	v_max_u32_e32 v24, v24, v25
	v_add_u32_e32 v49, v24, v48
	v_sub_u32_e32 v26, v88, v49
	v_sub_u32_e32 v27, v89, v49
	v_max_u32_e32 v24, v26, v27
	v_sub_u32_e32 v28, v164, v49
	v_sub_u32_e32 v29, v165, v49
	v_max3_u32 v24, v24, v28, v29
	v_sub_u32_e32 v30, v166, v49
	v_sub_u32_e32 v31, v167, v49
	v_max3_u32 v24, v24, v30, v31
	v_sub_u32_e32 v32, v168, v49
	v_sub_u32_e32 v33, v169, v49
	v_max3_u32 v24, v24, v32, v33
	v_sub_u32_e32 v26, v171, v49
	v_sub_u32_e32 v27, v172, v49
	v_max3_u32 v24, v24, v26, v27
	v_sub_u32_e32 v28, v173, v49
	v_sub_u32_e32 v29, v176, v49
	v_max3_u32 v24, v24, v28, v29
	v_sub_u32_e32 v30, v177, v49
	v_sub_u32_e32 v31, v178, v49
	v_max3_u32 v24, v24, v30, v31
	v_sub_u32_e32 v32, v179, v49
	v_sub_u32_e32 v33, v180, v49
	v_max3_u32 v24, v24, v32, v33
	v_sub_u32_e32 v26, v181, v49
	v_sub_u32_e32 v27, v182, v49
	v_max3_u32 v24, v24, v26, v27
	v_sub_u32_e32 v28, v183, v49
	v_sub_u32_e32 v29, v184, v49
	v_max3_u32 v24, v24, v28, v29
	v_sub_u32_e32 v30, v185, v49
	v_sub_u32_e32 v31, v186, v49
	v_max3_u32 v24, v24, v30, v31
	v_sub_u32_e32 v32, v187, v49
	v_sub_u32_e32 v33, v188, v49
	v_max3_u32 v24, v24, v32, v33
	v_sub_u32_e32 v26, v189, v49
	v_sub_u32_e32 v27, v194, v49
	v_max3_u32 v24, v24, v26, v27
	v_sub_u32_e32 v28, v195, v49
	v_sub_u32_e32 v29, v196, v49
	v_max3_u32 v24, v24, v28, v29
	v_sub_u32_e32 v30, v4, v49
	v_sub_u32_e32 v31, v1, v49
	v_max3_u32 v24, v24, v30, v31
	v_sub_u32_e32 v32, v2, v49
	v_sub_u32_e32 v33, v3, v49
	v_max3_u32 v24, v24, v32, v33
	v_mov_b32_e32 v25, v24
	s_nop 1
	v_permlane16_swap_b32 v24, v25
	s_nop 1
	v_max_u32_e32 v24, v24, v25
	v_mov_b32_e32 v25, v24
	s_nop 1
	v_permlane32_swap_b32 v24, v25
	s_nop 1
	v_max_u32_e32 v24, v24, v25
	v_add_u32_e32 v50, v24, v49
	v_sub_u32_e32 v26, v88, v50
	v_sub_u32_e32 v27, v89, v50
	v_max_u32_e32 v24, v26, v27
	v_sub_u32_e32 v28, v164, v50
	v_sub_u32_e32 v29, v165, v50
	v_max3_u32 v24, v24, v28, v29
	v_sub_u32_e32 v30, v166, v50
	v_sub_u32_e32 v31, v167, v50
	v_max3_u32 v24, v24, v30, v31
	v_sub_u32_e32 v32, v168, v50
	v_sub_u32_e32 v33, v169, v50
	v_max3_u32 v24, v24, v32, v33
	v_sub_u32_e32 v26, v171, v50
	v_sub_u32_e32 v27, v172, v50
	v_max3_u32 v24, v24, v26, v27
	v_sub_u32_e32 v28, v173, v50
	v_sub_u32_e32 v29, v176, v50
	v_max3_u32 v24, v24, v28, v29
	v_sub_u32_e32 v30, v177, v50
	v_sub_u32_e32 v31, v178, v50
	v_max3_u32 v24, v24, v30, v31
	v_sub_u32_e32 v32, v179, v50
	v_sub_u32_e32 v33, v180, v50
	v_max3_u32 v24, v24, v32, v33
	v_sub_u32_e32 v26, v181, v50
	v_sub_u32_e32 v27, v182, v50
	v_max3_u32 v24, v24, v26, v27
	v_sub_u32_e32 v28, v183, v50
	v_sub_u32_e32 v29, v184, v50
	v_max3_u32 v24, v24, v28, v29
	v_sub_u32_e32 v30, v185, v50
	v_sub_u32_e32 v31, v186, v50
	v_max3_u32 v24, v24, v30, v31
	v_sub_u32_e32 v32, v187, v50
	v_sub_u32_e32 v33, v188, v50
	v_max3_u32 v24, v24, v32, v33
	v_sub_u32_e32 v26, v189, v50
	v_sub_u32_e32 v27, v194, v50
	v_max3_u32 v24, v24, v26, v27
	v_sub_u32_e32 v28, v195, v50
	v_sub_u32_e32 v29, v196, v50
	v_max3_u32 v24, v24, v28, v29
	v_sub_u32_e32 v30, v4, v50
	v_sub_u32_e32 v31, v1, v50
	v_max3_u32 v24, v24, v30, v31
	v_sub_u32_e32 v32, v2, v50
	v_sub_u32_e32 v33, v3, v50
	v_max3_u32 v24, v24, v32, v33
; DI void peer_topk_wave(const Params& p, int item, unsigned* lds  ) {
;     ...
;     for (int rr = 0; rr < 16; ++rr) {
;       unsigned m = 0;
; #pragma unroll
;       for (int i = 0; i < 32; ++i) m = umax(m, kk[i]);
;       m = umax(m, (unsigned)__shfl_xor((int)m, 16));
;       m = umax(m, (unsigned)__shfl_xor((int)m, 32));
;       win[pp][rr] = m;
; #pragma unroll
;       for (int i = 0; i < 32; ++i) kk[i] = (kk[i] == m) ? 0u : kk[i];
	v_mov_b32_e32 v25, v24
	s_nop 1
	v_permlane16_swap_b32 v24, v25
	s_nop 1
	v_max_u32_e32 v24, v24, v25
	v_mov_b32_e32 v25, v24
	s_nop 1
	v_permlane32_swap_b32 v24, v25
	s_nop 1
	v_max_u32_e32 v24, v24, v25
	v_add_u32_e32 v51, v24, v50
	v_sub_u32_e32 v26, v88, v51
	v_sub_u32_e32 v27, v89, v51
	v_max_u32_e32 v24, v26, v27
	v_sub_u32_e32 v28, v164, v51
	v_sub_u32_e32 v29, v165, v51
	v_max3_u32 v24, v24, v28, v29
	v_sub_u32_e32 v30, v166, v51
	v_sub_u32_e32 v31, v167, v51
	v_max3_u32 v24, v24, v30, v31
	v_sub_u32_e32 v32, v168, v51
	v_sub_u32_e32 v33, v169, v51
	v_max3_u32 v24, v24, v32, v33
	v_sub_u32_e32 v26, v171, v51
	v_sub_u32_e32 v27, v172, v51
	v_max3_u32 v24, v24, v26, v27
	v_sub_u32_e32 v28, v173, v51
	v_sub_u32_e32 v29, v176, v51
	v_max3_u32 v24, v24, v28, v29
	v_sub_u32_e32 v30, v177, v51
	v_sub_u32_e32 v31, v178, v51
	v_max3_u32 v24, v24, v30, v31
	v_sub_u32_e32 v32, v179, v51
	v_sub_u32_e32 v33, v180, v51
	v_max3_u32 v24, v24, v32, v33
	v_sub_u32_e32 v26, v181, v51
	v_sub_u32_e32 v27, v182, v51
	v_max3_u32 v24, v24, v26, v27
	v_sub_u32_e32 v28, v183, v51
	v_sub_u32_e32 v29, v184, v51
	v_max3_u32 v24, v24, v28, v29
	v_sub_u32_e32 v30, v185, v51
	v_sub_u32_e32 v31, v186, v51
	v_max3_u32 v24, v24, v30, v31
	v_sub_u32_e32 v32, v187, v51
	v_sub_u32_e32 v33, v188, v51
	v_max3_u32 v24, v24, v32, v33
	v_sub_u32_e32 v26, v189, v51
	v_sub_u32_e32 v27, v194, v51
	v_max3_u32 v24, v24, v26, v27
	v_sub_u32_e32 v28, v195, v51
	v_sub_u32_e32 v29, v196, v51
	v_max3_u32 v24, v24, v28, v29
	v_sub_u32_e32 v30, v4, v51
	v_sub_u32_e32 v31, v1, v51
	v_max3_u32 v24, v24, v30, v31
	v_sub_u32_e32 v32, v2, v51
	v_sub_u32_e32 v33, v3, v51
	v_max3_u32 v24, v24, v32, v33
	v_mov_b32_e32 v25, v24
	s_nop 1
	v_permlane16_swap_b32 v24, v25
	s_nop 1
	v_max_u32_e32 v24, v24, v25
	v_mov_b32_e32 v25, v24
	s_nop 1
	v_permlane32_swap_b32 v24, v25
	s_nop 1
	v_max_u32_e32 v24, v24, v25
	v_add_u32_e32 v52, v24, v51
	v_sub_u32_e32 v26, v88, v52
	v_sub_u32_e32 v27, v89, v52
	v_max_u32_e32 v24, v26, v27
	v_sub_u32_e32 v28, v164, v52
	v_sub_u32_e32 v29, v165, v52
	v_max3_u32 v24, v24, v28, v29
	v_sub_u32_e32 v30, v166, v52
	v_sub_u32_e32 v31, v167, v52
	v_max3_u32 v24, v24, v30, v31
	v_sub_u32_e32 v32, v168, v52
	v_sub_u32_e32 v33, v169, v52
	v_max3_u32 v24, v24, v32, v33
	v_sub_u32_e32 v26, v171, v52
	v_sub_u32_e32 v27, v172, v52
	v_max3_u32 v24, v24, v26, v27
	v_sub_u32_e32 v28, v173, v52
	v_sub_u32_e32 v29, v176, v52
	v_max3_u32 v24, v24, v28, v29
	v_sub_u32_e32 v30, v177, v52
	v_sub_u32_e32 v31, v178, v52
	v_max3_u32 v24, v24, v30, v31
	v_sub_u32_e32 v32, v179, v52
	v_sub_u32_e32 v33, v180, v52
	v_max3_u32 v24, v24, v32, v33
	v_sub_u32_e32 v26, v181, v52
	v_sub_u32_e32 v27, v182, v52
	v_max3_u32 v24, v24, v26, v27
	v_sub_u32_e32 v28, v183, v52
	v_sub_u32_e32 v29, v184, v52
	v_max3_u32 v24, v24, v28, v29
	v_sub_u32_e32 v30, v185, v52
	v_sub_u32_e32 v31, v186, v52
	v_max3_u32 v24, v24, v30, v31
	v_sub_u32_e32 v32, v187, v52
	v_sub_u32_e32 v33, v188, v52
	v_max3_u32 v24, v24, v32, v33
	v_sub_u32_e32 v26, v189, v52
	v_sub_u32_e32 v27, v194, v52
	v_max3_u32 v24, v24, v26, v27
	v_sub_u32_e32 v28, v195, v52
	v_sub_u32_e32 v29, v196, v52
	v_max3_u32 v24, v24, v28, v29
	v_sub_u32_e32 v30, v4, v52
	v_sub_u32_e32 v31, v1, v52
	v_max3_u32 v24, v24, v30, v31
	v_sub_u32_e32 v32, v2, v52
	v_sub_u32_e32 v33, v3, v52
	v_max3_u32 v24, v24, v32, v33
	v_mov_b32_e32 v25, v24
	s_nop 1
	v_permlane16_swap_b32 v24, v25
	s_nop 1
	v_max_u32_e32 v24, v24, v25
	v_mov_b32_e32 v25, v24
	s_nop 1
	v_permlane32_swap_b32 v24, v25
	s_nop 1
	v_max_u32_e32 v24, v24, v25
	v_add_u32_e32 v53, v24, v52
	v_sub_u32_e32 v26, v88, v53
	v_sub_u32_e32 v27, v89, v53
	v_max_u32_e32 v24, v26, v27
	v_sub_u32_e32 v28, v164, v53
	v_sub_u32_e32 v29, v165, v53
	v_max3_u32 v24, v24, v28, v29
	v_sub_u32_e32 v30, v166, v53
	v_sub_u32_e32 v31, v167, v53
	v_max3_u32 v24, v24, v30, v31
	v_sub_u32_e32 v32, v168, v53
	v_sub_u32_e32 v33, v169, v53
	v_max3_u32 v24, v24, v32, v33
	v_sub_u32_e32 v26, v171, v53
	v_sub_u32_e32 v27, v172, v53
	v_max3_u32 v24, v24, v26, v27
	v_sub_u32_e32 v28, v173, v53
	v_sub_u32_e32 v29, v176, v53
; DI float unordf(unsigned k) { unsigned u = (k & 0x80000000u) ? (k & 0x7fffffffu) : ~k; return __uint_as_float(u); }
; DI void peer_topk_wave(const Params& p, int item, unsigned* lds  ) {
;     ...
;     for (int rr = 0; rr < 16; ++rr) {
;       unsigned m = 0;
; #pragma unroll
;       for (int i = 0; i < 32; ++i) m = umax(m, kk[i]);
;       m = umax(m, (unsigned)__shfl_xor((int)m, 16));
;       m = umax(m, (unsigned)__shfl_xor((int)m, 32));
;       win[pp][rr] = m;
; #pragma unroll
;       for (int i = 0; i < 32; ++i) kk[i] = (kk[i] == m) ? 0u : kk[i];
;     }
;   }
;   float f0[16], f1[16];
; #pragma unroll
;   for (int i = 0; i < 16; ++i) { f0[i] = unordf(win[0][i] & ~127u); f1[i] = unordf(win[1][i] & ~127u); }
	v_max3_u32 v24, v24, v28, v29
	v_sub_u32_e32 v30, v177, v53
	v_sub_u32_e32 v31, v178, v53
	v_max3_u32 v24, v24, v30, v31
	v_sub_u32_e32 v32, v179, v53
	v_sub_u32_e32 v33, v180, v53
	v_max3_u32 v24, v24, v32, v33
	v_sub_u32_e32 v26, v181, v53
	v_sub_u32_e32 v27, v182, v53
	v_max3_u32 v24, v24, v26, v27
	v_sub_u32_e32 v28, v183, v53
	v_sub_u32_e32 v29, v184, v53
	v_max3_u32 v24, v24, v28, v29
	v_sub_u32_e32 v30, v185, v53
	v_sub_u32_e32 v31, v186, v53
	v_max3_u32 v24, v24, v30, v31
	v_sub_u32_e32 v32, v187, v53
	v_sub_u32_e32 v33, v188, v53
	v_max3_u32 v24, v24, v32, v33
	v_sub_u32_e32 v26, v189, v53
	v_sub_u32_e32 v27, v194, v53
	v_max3_u32 v24, v24, v26, v27
	v_sub_u32_e32 v28, v195, v53
	v_sub_u32_e32 v29, v196, v53
	v_max3_u32 v24, v24, v28, v29
	v_sub_u32_e32 v30, v4, v53
	v_sub_u32_e32 v31, v1, v53
	v_max3_u32 v24, v24, v30, v31
	v_sub_u32_e32 v32, v2, v53
	v_sub_u32_e32 v33, v3, v53
	v_max3_u32 v24, v24, v32, v33
	v_mov_b32_e32 v25, v24
	s_nop 1
	v_permlane16_swap_b32 v24, v25
	s_nop 1
	v_max_u32_e32 v24, v24, v25
	v_mov_b32_e32 v25, v24
	s_nop 1
	v_permlane32_swap_b32 v24, v25
	s_nop 1
	v_max_u32_e32 v24, v24, v25
	v_add_u32_e32 v54, v24, v53
	v_sub_u32_e32 v26, v88, v54
	v_sub_u32_e32 v27, v89, v54
	v_max_u32_e32 v24, v26, v27
	v_sub_u32_e32 v28, v164, v54
	v_sub_u32_e32 v29, v165, v54
	v_max3_u32 v24, v24, v28, v29
	v_sub_u32_e32 v30, v166, v54
	v_sub_u32_e32 v31, v167, v54
	v_max3_u32 v24, v24, v30, v31
	v_sub_u32_e32 v32, v168, v54
	v_sub_u32_e32 v33, v169, v54
	v_max3_u32 v24, v24, v32, v33
	v_sub_u32_e32 v26, v171, v54
	v_sub_u32_e32 v27, v172, v54
	v_max3_u32 v24, v24, v26, v27
	v_sub_u32_e32 v28, v173, v54
	v_sub_u32_e32 v29, v176, v54
	v_max3_u32 v24, v24, v28, v29
	v_sub_u32_e32 v30, v177, v54
	v_sub_u32_e32 v31, v178, v54
	v_max3_u32 v24, v24, v30, v31
	v_sub_u32_e32 v32, v179, v54
	v_sub_u32_e32 v33, v180, v54
	v_max3_u32 v24, v24, v32, v33
	v_sub_u32_e32 v26, v181, v54
	v_sub_u32_e32 v27, v182, v54
	v_max3_u32 v24, v24, v26, v27
	v_sub_u32_e32 v28, v183, v54
	v_sub_u32_e32 v29, v184, v54
	v_max3_u32 v24, v24, v28, v29
	v_sub_u32_e32 v30, v185, v54
	v_sub_u32_e32 v31, v186, v54
	v_max3_u32 v24, v24, v30, v31
	v_sub_u32_e32 v32, v187, v54
	v_sub_u32_e32 v33, v188, v54
	v_max3_u32 v24, v24, v32, v33
	v_sub_u32_e32 v26, v189, v54
	v_sub_u32_e32 v27, v194, v54
	v_max3_u32 v24, v24, v26, v27
	v_sub_u32_e32 v28, v195, v54
	v_sub_u32_e32 v29, v196, v54
	v_max3_u32 v24, v24, v28, v29
	v_sub_u32_e32 v30, v4, v54
	v_sub_u32_e32 v31, v1, v54
	v_max3_u32 v24, v24, v30, v31
	v_sub_u32_e32 v32, v2, v54
	v_sub_u32_e32 v33, v3, v54
	v_max3_u32 v24, v24, v32, v33
	v_mov_b32_e32 v25, v24
	s_nop 1
	v_permlane16_swap_b32 v24, v25
	s_nop 1
	v_max_u32_e32 v24, v24, v25
	v_mov_b32_e32 v25, v24
	s_nop 1
	v_permlane32_swap_b32 v24, v25
	s_nop 1
	v_max_u32_e32 v24, v24, v25
	v_add_u32_e32 v55, v24, v54
	v_mov_b32_e32 v0, v40
	v_mov_b32_e32 v1, v41
	v_mov_b32_e32 v2, v42
	v_mov_b32_e32 v3, v43
	v_mov_b32_e32 v4, v44
	v_mov_b32_e32 v5, v45
	v_mov_b32_e32 v6, v46
	v_mov_b32_e32 v7, v47
	v_mov_b32_e32 v8, v48
	v_mov_b32_e32 v9, v49
	v_mov_b32_e32 v10, v50
	v_mov_b32_e32 v11, v51
	v_mov_b32_e32 v12, v52
	v_mov_b32_e32 v13, v53
	v_mov_b32_e32 v14, v54
	v_mov_b32_e32 v15, v55
	v_bitop3_b32 v87, v0, s81, v0 bitop3:0xcf
	ds_bpermute_b32 v86, v111, v15
	v_cmp_gt_i32_e32 vcc, 0, v0
	s_waitcnt lgkmcnt(0)
	v_max_u32_e32 v15, v15, v86
	ds_bpermute_b32 v166, v112, v15
	v_and_b32_e32 v86, 0x7fffff80, v0
	v_cndmask_b32_e32 v89, v87, v86, vcc
	v_and_b32_e32 v86, 0x7fffff80, v1
	v_bitop3_b32 v87, v1, s81, v1 bitop3:0xcf
	v_cmp_gt_i32_e32 vcc, 0, v1
	s_nop 1
	v_cndmask_b32_e32 v164, v87, v86, vcc
	v_cmp_lt_i32_e32 vcc, 0, v175
	v_mov_b32_e32 v86, v89
	s_and_saveexec_b64 s[0:1], vcc
	s_cbranch_execz .LBB0_1097
	v_cmp_ne_u32_e32 vcc, 1, v175
	s_and_saveexec_b64 s[2:3], vcc
	s_xor_b64 s[2:3], exec, s[2:3]
	v_cndmask_b32_e64 v86, v164, v89, s[10:11]
	s_andn2_saveexec_b64 s[2:3], s[2:3]
	v_and_b32_e32 v86, 0x7fffff80, v13
	v_bitop3_b32 v87, v13, s81, v13 bitop3:0xcf
	v_cmp_gt_i32_e32 vcc, 0, v13
	s_nop 1
	v_cndmask_b32_e32 v86, v87, v86, vcc
	s_or_b64 exec, exec, s[2:3]
